# g2m2 + remaining packed f32 mul/add/fma (weight copy, final norm, prep, unit merges) as scalar pairs
# speedup vs baseline: 1.0017x; 1.0017x over previous
.LBB0_308:
	s_lshl_b32 s8, s73, 8
	s_and_b32 s6, s73, 0xfffffe
	s_cmp_eq_u32 s6, 6
	v_cmp_lt_i32_e32 vcc, s8, v89
	s_cselect_b64 s[6:7], -1, 0
	s_or_b64 vcc, vcc, s[6:7]
	v_cndmask_b32_e32 v70, 1.0, v184, vcc
	v_cndmask_b32_e64 v71, v70, 1.0, s[46:47]
	v_mul_f32_e32 v70, v71, v103
	v_mul_f32_e32 v118, v28, v70
	v_mul_f32_e32 v119, v29, v70
	v_mul_f32_e32 v116, v26, v70
	v_mul_f32_e32 v117, v27, v70
	v_mul_f32_e32 v70, v71, v105
	ds_write_b128 v114, v[116:119]
	v_mul_f32_e32 v116, v32, v70
	v_mul_f32_e32 v117, v33, v70
	v_mul_f32_e32 v114, v30, v70
	v_mul_f32_e32 v115, v31, v70
	v_mul_f32_e32 v70, v71, v106
	ds_write_b128 v95, v[114:117] offset:8320
	v_pk_mul_f32 v[116:117], v[70:71], v[40:41] op_sel_hi:[0,1]
	v_pk_mul_f32 v[114:115], v[70:71], v[38:39] op_sel_hi:[0,1]
	v_mul_f32_e32 v70, v71, v108
	ds_write_b128 v96, v[114:117] offset:16640
	v_pk_mul_f32 v[116:117], v[70:71], v[44:45] op_sel_hi:[0,1]
	v_pk_mul_f32 v[114:115], v[70:71], v[42:43] op_sel_hi:[0,1]
	v_mul_f32_e32 v70, v71, v109
	ds_write_b128 v97, v[114:117] offset:24960
	v_pk_mul_f32 v[116:117], v[70:71], v[52:53] op_sel_hi:[0,1]
	v_pk_mul_f32 v[114:115], v[70:71], v[50:51] op_sel_hi:[0,1]
	v_mul_f32_e32 v70, v71, v111
	ds_write_b128 v98, v[114:117] offset:33280
	v_pk_mul_f32 v[116:117], v[70:71], v[56:57] op_sel_hi:[0,1]
	v_pk_mul_f32 v[114:115], v[70:71], v[54:55] op_sel_hi:[0,1]
	v_mul_f32_e32 v70, v71, v112
	ds_write_b128 v99, v[114:117] offset:41600
	v_pk_mul_f32 v[116:117], v[70:71], v[60:61] op_sel_hi:[0,1]
	v_pk_mul_f32 v[114:115], v[70:71], v[58:59] op_sel_hi:[0,1]
	v_mul_f32_e32 v70, v71, v113
	ds_write_b128 v100, v[114:117] offset:49920
	v_pk_mul_f32 v[116:117], v[70:71], v[64:65] op_sel_hi:[0,1]
	v_pk_mul_f32 v[114:115], v[70:71], v[62:63] op_sel_hi:[0,1]
	v_add_u32_e32 v70, s8, v85
	v_cmp_gt_i32_e32 vcc, s71, v70
	ds_write_b128 v101, v[114:117] offset:58240
	s_waitcnt lgkmcnt(0)
	s_barrier
	s_and_saveexec_b64 s[6:7], vcc
	s_cbranch_execz .LBB0_310
	ds_read_b32 v71, v91 offset:6240
	ds_read_b32 v114, v91 offset:7280
	ds_read_b32 v115, v91 offset:4160
	ds_read_b32 v116, v91 offset:5200
	ds_read_b32 v118, v91 offset:2080
	ds_read_b32 v119, v91 offset:3120
	ds_read_b32 v120, v91
	ds_read_b32 v121, v91 offset:1040
	s_waitcnt lgkmcnt(6)
	v_cvt_pk_bf16_f32 v117, v71, v114
	v_ashrrev_i32_e32 v71, 31, v70
	s_waitcnt lgkmcnt(4)
	v_cvt_pk_bf16_f32 v116, v115, v116
	s_waitcnt lgkmcnt(2)
	v_cvt_pk_bf16_f32 v115, v118, v119
	v_mul_lo_u32 v118, s41, v70
	v_mul_lo_u32 v119, s40, v71
	v_mad_u64_u32 v[70:71], s[46:47], s40, v70, 0
	v_add3_u32 v71, v71, v119, v118
	v_lshl_add_u64 v[70:71], v[70:71], 1, s[42:43]
	s_lshl_b32 s46, s72, 6
	v_lshl_add_u64 v[70:71], s[44:45], 1, v[70:71]
	s_ashr_i32 s47, s46, 31
	v_lshl_add_u64 v[70:71], s[46:47], 1, v[70:71]
	s_waitcnt lgkmcnt(0)
	v_cvt_pk_bf16_f32 v114, v120, v121
	v_lshl_add_u64 v[70:71], v[70:71], 0, v[0:1]
	global_store_dwordx4 v[70:71], v[114:117], off

.LBB0_323:
	global_load_dwordx4 v[12:15], v[8:9], off offset:-12
	global_load_dwordx4 v[16:19], v[8:9], off offset:-28
	global_load_dwordx4 v[20:23], v[8:9], off offset:-60
	global_load_dwordx4 v[24:27], v[8:9], off offset:-44
	s_movk_i32 s0, 0xe000
	v_add_co_u32_e64 v34, s[0:1], s0, v6
	s_movk_i32 s26, 0xf000
	s_nop 0
	v_addc_co_u32_e64 v35, s[0:1], -1, v7, s[0:1]
	v_add_co_u32_e32 v28, vcc, 0xffffd000, v6
	v_add_co_u32_e64 v36, s[0:1], s26, v6
	s_nop 0
	v_addc_co_u32_e32 v29, vcc, -1, v7, vcc
	v_addc_co_u32_e64 v37, s[0:1], -1, v7, s[0:1]
	global_load_dword v30, v[6:7], off offset:-4096
	global_load_dword v31, v[6:7], off offset:-3072
	global_load_dword v32, v[6:7], off offset:-2048
	global_load_dword v39, v[36:37], off offset:-3072
	global_load_dword v40, v[36:37], off offset:-2048
	global_load_dword v41, v[36:37], off offset:-1024
	global_load_dword v11, v[28:29], off offset:-3072
	global_load_dword v42, v[28:29], off offset:-2048
	global_load_dword v43, v[28:29], off offset:-1024
	s_nop 0
	global_load_dword v28, v[28:29], off
	s_nop 0
	global_load_dword v29, v[34:35], off offset:-3072
	global_load_dword v36, v[34:35], off offset:-2048
	global_load_dword v37, v[34:35], off offset:-1024
	global_load_dword v38, v[34:35], off
	global_load_dword v33, v[6:7], off offset:-1024
	global_load_dword v44, v[6:7], off
	s_add_i32 s25, s25, 16
	v_lshl_add_u64 v[8:9], v[8:9], 0, 64
	v_lshl_add_u64 v[6:7], v[6:7], 0, s[68:69]
	s_cmp_gt_u32 s25, 47
	s_waitcnt vmcnt(17)
	v_mov_b32_e32 v34, v23
	s_waitcnt vmcnt(16)
	v_mov_b32_e32 v35, v24
	v_mov_b32_e32 v24, v25
	v_mov_b32_e32 v25, v26
	v_mov_b32_e32 v26, v27
	v_mov_b32_e32 v27, v16
	v_mov_b32_e32 v16, v17
	v_mov_b32_e32 v17, v18
	s_waitcnt vmcnt(9)
	v_fmac_f32_e32 v10, v11, v20
	s_waitcnt vmcnt(8)
	v_fmac_f32_e32 v10, v42, v21
	s_waitcnt vmcnt(7)
	v_fmac_f32_e32 v10, v43, v22
	v_mul_f32_e32 v16, v40, v16
	v_mul_f32_e32 v17, v41, v17
	s_waitcnt vmcnt(5)
	v_mul_f32_e32 v28, v28, v34
	v_mul_f32_e32 v29, v29, v35
	v_mov_b32_e32 v18, v19
	v_add_f32_e32 v10, v10, v28
	s_waitcnt vmcnt(3)
	v_mul_f32_e32 v24, v36, v24
	v_mul_f32_e32 v25, v37, v25
	v_add_f32_e32 v10, v10, v29
	v_add_f32_e32 v10, v10, v24
	s_waitcnt vmcnt(2)
	v_mul_f32_e32 v26, v38, v26
	v_mul_f32_e32 v27, v39, v27
	v_add_f32_e32 v10, v10, v25
	v_add_f32_e32 v10, v10, v26
	v_add_f32_e32 v10, v10, v27
	v_mov_b32_e32 v19, v12
	v_add_f32_e32 v10, v10, v16
	v_mul_f32_e32 v18, v30, v18
	v_mul_f32_e32 v19, v31, v19
	v_add_f32_e32 v10, v10, v17
	v_mov_b32_e32 v12, v13
	v_mov_b32_e32 v13, v14
	v_add_f32_e32 v10, v10, v18
	s_waitcnt vmcnt(1)
	v_mul_f32_e32 v12, v32, v12
	v_mul_f32_e32 v13, v33, v13
	v_add_f32_e32 v10, v10, v19
	v_add_f32_e32 v10, v10, v12
	v_add_f32_e32 v10, v10, v13
	s_waitcnt vmcnt(0)
	v_fmac_f32_e32 v10, v44, v15
	s_cbranch_scc0 .LBB0_323
	s_and_saveexec_b64 s[0:1], s[6:7]
	ds_write_b32 v0, v10
	s_or_b64 exec, exec, s[0:1]
	s_waitcnt lgkmcnt(0)
	s_barrier
	s_and_saveexec_b64 s[0:1], s[8:9]
	s_cbranch_execz .LBB0_321
	ds_read_b32 v8, v0
	v_lshl_or_b32 v6, s24, 8, v69
	v_ashrrev_i32_e32 v7, 31, v6
	v_lshl_add_u64 v[6:7], v[6:7], 2, s[10:11]
	s_waitcnt lgkmcnt(0)
	v_add_f32_e32 v8, v10, v8
	global_store_dword v[6:7], v8, off
	s_branch .LBB0_321

.LBB0_571:
	s_and_b32 s42, s48, 0x1e00
	s_ashr_i32 s40, s50, 4
	v_add_u32_e32 v2, s42, v35
	s_and_b32 s42, s27, 0xffffe000
	s_and_b32 s41, s40, 7
	v_add_u32_e32 v3, s42, v2
	v_mov_b64_e32 v[14:15], s[30:31]
	v_mad_i64_i32 v[14:15], s[42:43], v3, s90, v[14:15]
	s_lshl_b32 s80, s41, 1
	v_lshl_add_u64 v[14:15], v[14:15], 0, s[80:81]
	s_or_b32 s80, s41, s33
	v_add_co_u32_e32 v14, vcc, 0x2000, v14
	s_lshl_b64 s[42:43], s[80:81], 2
	s_nop 0
	v_addc_co_u32_e32 v15, vcc, 0, v15, vcc
	s_waitcnt lgkmcnt(0)
	s_add_u32 s42, s0, s42
	global_load_ushort v3, v[14:15], off offset:1536
	s_addc_u32 s43, s1, s43
	global_load_dword v13, v1, s[42:43]
	s_mov_b32 s41, 0xbfb8aa3b
	s_waitcnt vmcnt(1)
	v_lshlrev_b32_e32 v3, 16, v3
	s_waitcnt vmcnt(0)
	v_add_f32_e32 v13, v13, v3
	v_min_f32_e32 v3, 0, v13
	v_mul_f32_e64 v13, |v13|, s41
	v_exp_f32_e32 v13, v13
	s_mov_b32 s41, 0x3f2aaaab
	v_add_f32_e32 v16, 1.0, v13
	v_add_f32_e32 v14, -1.0, v16
	v_sub_f32_e32 v15, v14, v16
	v_add_f32_e32 v15, 1.0, v15
	v_sub_f32_e32 v14, v13, v14
	v_add_f32_e32 v17, v14, v15
	v_frexp_mant_f32_e32 v14, v16
	v_cmp_gt_f32_e32 vcc, s41, v14
	v_cvt_f64_f32_e32 v[14:15], v16
	v_frexp_exp_i32_f64_e32 v14, v[14:15]
	v_subbrev_co_u32_e32 v22, vcc, 0, v14, vcc
	v_sub_u32_e32 v14, 0, v22
	v_ldexp_f32 v15, v16, v14
	v_add_f32_e32 v16, -1.0, v15
	v_add_f32_e32 v18, 1.0, v15
	v_ldexp_f32 v14, v17, v14
	v_add_f32_e32 v17, 1.0, v16
	v_add_f32_e32 v19, -1.0, v18
	v_sub_f32_e32 v17, v15, v17
	v_sub_f32_e32 v15, v15, v19
	v_add_f32_e32 v17, v14, v17
	v_add_f32_e32 v14, v14, v15
	v_add_f32_e32 v23, v18, v14
	v_rcp_f32_e32 v25, v23
	v_sub_f32_e32 v15, v23, v18
	v_sub_f32_e32 v24, v14, v15
	v_add_f32_e32 v15, v16, v17
	v_mul_f32_e32 v27, v15, v25
	v_sub_f32_e32 v14, v15, v16
	v_mul_f32_e32 v16, v23, v27
	v_fma_f32 v18, v27, v23, -v16
	v_fmac_f32_e32 v18, v27, v24
	v_sub_f32_e32 v26, v17, v14
	v_add_f32_e32 v14, v16, v18
	v_sub_f32_e32 v17, v15, v14
	v_pk_add_f32 v[20:21], v[14:15], v[16:17] neg_lo:[0,1] neg_hi:[0,1]
	v_mov_b32_e32 v19, v14
	v_pk_add_f32 v[14:15], v[20:21], v[18:19] neg_lo:[0,1] neg_hi:[0,1]
	s_mov_b32 s41, 0x3f317218
	v_add_f32_e32 v15, v26, v15
	v_add_f32_e32 v14, v14, v15
	v_add_f32_e32 v15, v17, v14
	v_mul_f32_e32 v26, v25, v15
	v_mul_f32_e32 v16, v23, v26
	v_fma_f32 v18, v26, v23, -v16
	v_fmac_f32_e32 v18, v26, v24
	v_sub_f32_e32 v17, v17, v15
	v_add_f32_e32 v23, v14, v17
	v_add_f32_e32 v14, v16, v18
	v_sub_f32_e32 v17, v15, v14
	v_pk_add_f32 v[20:21], v[14:15], v[16:17] neg_lo:[0,1] neg_hi:[0,1]
	v_mov_b32_e32 v19, v14
	v_pk_add_f32 v[14:15], v[20:21], v[18:19] neg_lo:[0,1] neg_hi:[0,1]
	s_nop 0
	v_add_f32_e32 v15, v23, v15
	v_add_f32_e32 v14, v14, v15
	v_add_f32_e32 v15, v27, v26
	v_add_f32_e32 v14, v17, v14
	v_sub_f32_e32 v16, v15, v27
	v_mul_f32_e32 v14, v25, v14
	v_sub_f32_e32 v16, v26, v16
	v_add_f32_e32 v16, v16, v14
	v_add_f32_e32 v18, v15, v16
	v_mul_f32_e32 v19, v18, v18
	v_mov_b32_e32 v14, 0x3ecc95a3
	v_fmamk_f32 v14, v19, 0x3e9b6dac, v14
	v_fmaak_f32 v161, v19, v14, 0x3f2aaada
	v_cvt_f32_i32_e32 v14, v22
	v_sub_f32_e32 v15, v18, v15
	v_sub_f32_e32 v15, v16, v15
	v_ldexp_f32 v20, v15, 1
	v_mul_f32_e32 v15, v18, v19
	v_ldexp_f32 v17, v18, 1
	v_mul_f32_e32 v18, v14, v160
	v_mul_f32_e32 v19, v15, v161
	s_nop 0
	v_fma_f32 v16, v14, s41, -v18
	v_fmac_f32_e32 v16, 0xb102e308, v14
	v_add_f32_e32 v14, v18, v16
	v_add_f32_e32 v15, v19, v17
	s_mov_b32 s41, 0x7f800000
	v_sub_f32_e32 v17, v15, v17
	v_sub_f32_e32 v17, v19, v17
	v_add_f32_e32 v21, v20, v17
	v_mov_b32_e32 v20, v18
	v_pk_add_f32 v[18:19], v[14:15], v[18:19] neg_lo:[0,1] neg_hi:[0,1]
	v_add_f32_e32 v22, v14, v20
	v_add_f32_e32 v23, v15, v21
	v_mov_b32_e32 v17, v14
	v_mov_b32_e32 v19, v23
	v_pk_add_f32 v[24:25], v[16:17], v[18:19] neg_lo:[0,1] neg_hi:[0,1]
	v_add_f32_e32 v16, v16, v18
	v_add_f32_e32 v17, v17, v19
	v_mov_b32_e32 v20, v21
	v_pk_add_f32 v[18:19], v[16:17], v[14:15] op_sel:[1,0] op_sel_hi:[0,1] neg_lo:[0,1] neg_hi:[0,1]
	v_pk_add_f32 v[26:27], v[22:23], v[18:19] op_sel_hi:[1,0] neg_lo:[0,1] neg_hi:[0,1]
	v_mov_b32_e32 v22, v23
	v_mov_b32_e32 v23, v17
	v_pk_mov_b32 v[18:19], v[14:15], v[18:19] op_sel:[1,0]
	v_mov_b32_e32 v21, v14
	v_pk_add_f32 v[18:19], v[22:23], v[18:19] neg_lo:[0,1] neg_hi:[0,1]
	v_mov_b32_e32 v26, v24
	v_pk_add_f32 v[14:15], v[20:21], v[18:19] neg_lo:[0,1] neg_hi:[0,1]
	v_mov_b32_e32 v25, v17
	v_add_f32_e32 v18, v26, v14
	v_add_f32_e32 v19, v27, v15
	v_cmp_neq_f32_e32 vcc, s41, v13
	v_pk_add_f32 v[20:21], v[18:19], v[18:19] op_sel:[0,1] op_sel_hi:[1,0]
	s_mov_b32 s41, 0x33800000
	v_pk_add_f32 v[16:17], v[16:17], v[20:21] op_sel:[1,0] op_sel_hi:[0,1]
	v_mov_b32_e32 v19, v16
	v_pk_add_f32 v[22:23], v[18:19], v[24:25] neg_lo:[0,1] neg_hi:[0,1]
	v_mov_b32_e32 v15, v20
	v_sub_f32_e32 v17, v18, v22
	v_pk_add_f32 v[14:15], v[14:15], v[22:23] neg_lo:[0,1] neg_hi:[0,1]
	v_sub_f32_e32 v17, v24, v17
	v_add_f32_e32 v14, v14, v17
	v_add_f32_e32 v14, v14, v15
	v_add_f32_e32 v14, v16, v14
	v_mov_b32_e32 v15, 0x7f800000
	v_cndmask_b32_e32 v14, v15, v14, vcc
	v_cmp_ngt_f32_e32 vcc, -1.0, v13
	v_mov_b32_e32 v15, 0x7fc00000
	s_nop 0
	v_cndmask_b32_e32 v14, v15, v14, vcc
	v_cmp_neq_f32_e32 vcc, -1.0, v13
	s_nop 1
	v_cndmask_b32_e32 v14, v185, v14, vcc
	v_cmp_lt_f32_e64 vcc, |v13|, s41
	s_nop 1
	v_cndmask_b32_e32 v13, v14, v13, vcc
	v_sub_f32_e32 v3, v3, v13
	ds_write_b32 v0, v3
	s_waitcnt lgkmcnt(0)
	s_barrier
	ds_read_b32 v3, v0
	s_and_saveexec_b64 s[42:43], s[8:9]
	s_cbranch_execz .LBB0_573
	ds_read_b32 v13, v4
	s_waitcnt lgkmcnt(0)
	v_add_f32_e32 v3, v3, v13

.LBB0_600:
	s_or_b64 exec, exec, s[6:7]
	v_mov_b64_e32 v[4:5], s[30:31]
	v_mad_i64_i32 v[4:5], s[6:7], v11, s90, v[4:5]
	v_ashrrev_i32_e32 v3, 31, v2
	v_lshl_add_u64 v[12:13], v[2:3], 1, v[4:5]
	global_load_dwordx4 v[6:9], v[12:13], off
	global_load_dwordx4 v[2:5], v[12:13], off offset:16
	v_and_b32_e32 v11, 0x1fff, v11
	v_cvt_f32_u32_e32 v11, v11
	v_add_u32_e32 v0, s10, v0
	s_mov_b32 s6, 0x2ffff
	v_cmp_lt_i32_e32 vcc, s6, v0
	v_mul_f32_e32 v15, 0x3e4693b0, v11
	v_mul_f32_e32 v14, 0.15915494, v11
	v_mul_f32_e32 v17, 0x3d1a08c9, v11
	v_mul_f32_e32 v18, 0x3beef750, v11
	v_mul_f32_e32 v16, 0.15915494, v15
	v_mul_f32_e32 v19, 0x3ab95d24, v11
	v_mul_f32_e32 v20, 0x398fc8fc, v11
	v_rndne_f32_e32 v14, v14
	v_mul_f32_e32 v21, 0.15915494, v17
	v_mul_f32_e32 v22, 0.15915494, v18
	v_rndne_f32_e32 v16, v16
	v_mul_f32_e32 v23, 0.15915494, v19
	v_mul_f32_e32 v24, 0.15915494, v20
	v_fmamk_f32 v25, v14, 0xc0c90fdb, v11
	v_rndne_f32_e32 v21, v21
	v_rndne_f32_e32 v22, v22
	v_fmac_f32_e32 v15, 0xc0c90fdb, v16
	v_rndne_f32_e32 v23, v23
	v_rndne_f32_e32 v24, v24
	v_fmac_f32_e32 v25, 0x343bbd2e, v14
	v_fmac_f32_e32 v17, 0xc0c90fdb, v21
	v_fmac_f32_e32 v18, 0xc0c90fdb, v22
	v_fmac_f32_e32 v15, 0x343bbd2e, v16
	v_fmac_f32_e32 v19, 0xc0c90fdb, v23
	v_fmac_f32_e32 v20, 0xc0c90fdb, v24
	v_mul_f32_e32 v25, 0.15915494, v25
	v_fmac_f32_e32 v17, 0x343bbd2e, v21
	v_fmac_f32_e32 v18, 0x343bbd2e, v22
	v_mul_f32_e32 v21, 0.15915494, v15
	v_fmac_f32_e32 v19, 0x343bbd2e, v23
	v_fmac_f32_e32 v20, 0x343bbd2e, v24
	v_sin_f32_e32 v16, v25
	v_mul_f32_e32 v22, 0.15915494, v17
	v_mul_f32_e32 v23, 0.15915494, v18
	v_sin_f32_e32 v17, v21
	v_cos_f32_e32 v14, v25
	v_mul_f32_e32 v24, 0.15915494, v19
	v_mul_f32_e32 v25, 0.15915494, v20
	v_cos_f32_e32 v15, v21
	v_cos_f32_e32 v18, v22
	v_sin_f32_e32 v20, v22
	v_cos_f32_e32 v19, v23
	v_sin_f32_e32 v21, v23
	v_mul_f32_e32 v42, 0x385f10c8, v11
	v_mul_f32_e32 v11, 0x372d07a6, v11
	v_cos_f32_e32 v22, v24
	v_sin_f32_e32 v24, v24
	v_cos_f32_e32 v23, v25
	v_sin_f32_e32 v25, v25
	s_or_b64 s[4:5], vcc, s[4:5]
	v_add_u32_e32 v10, s11, v10
	s_waitcnt vmcnt(1)
	v_lshlrev_b32_e32 v26, 16, v6
	s_waitcnt vmcnt(0)
	v_lshlrev_b32_e32 v28, 16, v2
	v_and_b32_e32 v29, 0xffff0000, v2
	v_and_b32_e32 v27, 0xffff0000, v6
	v_lshlrev_b32_e32 v2, 16, v3
	v_and_b32_e32 v3, 0xffff0000, v3
	v_mul_f32_e32 v36, v16, v28
	v_mul_f32_e32 v37, v17, v29
	v_lshlrev_b32_e32 v6, 16, v7
	v_and_b32_e32 v7, 0xffff0000, v7
	v_mul_f32_e32 v28, v14, v28
	v_mul_f32_e32 v29, v15, v29
	v_mul_f32_e32 v38, v20, v2
	v_mul_f32_e32 v39, v21, v3
	v_mul_f32_e32 v2, v18, v2
	v_mul_f32_e32 v3, v19, v3
	v_pk_fma_f32 v[14:15], v[14:15], v[26:27], v[36:37] neg_lo:[0,0,1] neg_hi:[0,0,1]
	v_pk_fma_f32 v[18:19], v[18:19], v[6:7], v[38:39] neg_lo:[0,0,1] neg_hi:[0,0,1]
	v_fma_f32 v20, v20, v6, v2
	v_fma_f32 v21, v21, v7, v3
	v_cvt_pk_bf16_f32 v6, v14, v15
	v_mul_f32_e32 v14, 0.15915494, v42
	v_rndne_f32_e32 v14, v14
	v_fmac_f32_e32 v42, 0xc0c90fdb, v14
	v_fmac_f32_e32 v42, 0x343bbd2e, v14
	v_fma_f32 v16, v16, v26, v28
	v_fma_f32 v17, v17, v27, v29
	v_mul_f32_e32 v15, 0.15915494, v42
	v_cvt_pk_bf16_f32 v2, v16, v17
	v_cos_f32_e32 v14, v15
	v_sin_f32_e32 v16, v15
	v_mul_f32_e32 v15, 0.15915494, v11
	v_rndne_f32_e32 v15, v15
	v_fmac_f32_e32 v11, 0xc0c90fdb, v15
	v_fmac_f32_e32 v11, 0x343bbd2e, v15
	v_mul_f32_e32 v11, 0.15915494, v11
	v_sin_f32_e32 v17, v11
	v_lshlrev_b32_e32 v32, 16, v4
	v_and_b32_e32 v33, 0xffff0000, v4
	v_cos_f32_e32 v15, v11
	v_lshlrev_b32_e32 v30, 16, v8
	v_and_b32_e32 v31, 0xffff0000, v8
	v_mul_f32_e32 v40, v24, v32
	v_mul_f32_e32 v41, v25, v33
	v_mul_f32_e32 v32, v22, v32
	v_mul_f32_e32 v33, v23, v33
	v_pk_fma_f32 v[22:23], v[22:23], v[30:31], v[40:41] neg_lo:[0,0,1] neg_hi:[0,0,1]
	v_cvt_pk_bf16_f32 v3, v20, v21
	v_lshlrev_b32_e32 v20, 16, v5
	v_and_b32_e32 v21, 0xffff0000, v5
	v_cvt_pk_bf16_f32 v7, v18, v19
	v_cvt_pk_bf16_f32 v8, v22, v23
	v_lshlrev_b32_e32 v18, 16, v9
	v_and_b32_e32 v19, 0xffff0000, v9
	v_mul_f32_e32 v22, v16, v20
	v_mul_f32_e32 v23, v17, v21
	v_fma_f32 v24, v24, v30, v32
	v_fma_f32 v25, v25, v31, v33
	v_pk_fma_f32 v[22:23], v[14:15], v[18:19], v[22:23] neg_lo:[0,0,1] neg_hi:[0,0,1]
	v_mul_f32_e32 v14, v14, v20
	v_mul_f32_e32 v15, v15, v21
	v_cvt_pk_bf16_f32 v9, v22, v23
	v_fma_f32 v14, v16, v18, v14
	v_fma_f32 v15, v17, v19, v15
	v_cvt_pk_bf16_f32 v4, v24, v25
	v_cvt_pk_bf16_f32 v5, v14, v15
	global_store_dwordx4 v[12:13], v[6:9], off
	global_store_dwordx4 v[12:13], v[2:5], off offset:16
	s_andn2_b64 exec, exec, s[4:5]
	s_cbranch_execz .LBB0_609

.LBB0_686:
	s_waitcnt lgkmcnt(0)
	s_barrier
	ds_read_b32 v0, v167 offset:24832
	s_and_b64 s[0:1], s[24:25], s[6:7]
	v_add_u32_e32 v4, s34, v168
	s_and_saveexec_b64 s[4:5], s[0:1]
	s_cbranch_execz .LBB0_688
	s_waitcnt lgkmcnt(0)
	v_lshl_add_u32 v0, v4, 4, 31
	v_cvt_f32_i32_e32 v0, v0
	ds_read2_b32 v[2:3], v197 offset0:64 offset1:72
	v_mul_f32_e32 v0, v161, v0
	v_mul_f32_e32 v5, 0.15915494, v0
	v_rndne_f32_e32 v5, v5
	v_fmac_f32_e32 v0, 0xc0c90fdb, v5
	v_fmac_f32_e32 v0, 0x343bbd2e, v5
	v_mul_f32_e32 v0, 0.15915494, v0
	v_cos_f32_e32 v6, v0
	v_sin_f32_e32 v7, v0
	v_mov_b32_e32 v11, v6
	v_mov_b32_e32 v10, v7
	s_waitcnt lgkmcnt(0)
	v_mul_f32_e32 v8, v6, v2
	v_mul_f32_e32 v9, v7, v3
	v_mul_f32_e32 v2, v10, v2
	v_mul_f32_e32 v3, v11, v3
	v_sub_f32_e32 v0, v8, v9
	v_add_f32_e32 v2, v2, v3
	v_cndmask_b32_e64 v0, v2, v0, s[8:9]

.LBB0_691:
	s_waitcnt lgkmcnt(0)
	v_lshl_add_u32 v0, v4, 4, 31
	v_cvt_f32_i32_e32 v0, v0
	ds_read2_b32 v[8:9], v198 offset0:64 offset1:72
	v_mul_f32_e32 v0, v161, v0
	v_mul_f32_e32 v5, 0.15915494, v0
	v_rndne_f32_e32 v5, v5
	v_fmac_f32_e32 v0, 0xc0c90fdb, v5
	v_fmac_f32_e32 v0, 0x343bbd2e, v5
	v_mul_f32_e32 v0, 0.15915494, v0
	v_cos_f32_e32 v10, v0
	v_sin_f32_e32 v11, v0
	v_mov_b32_e32 v15, v10
	v_mov_b32_e32 v14, v11
	s_waitcnt lgkmcnt(0)
	v_mul_f32_e32 v12, v10, v8
	v_mul_f32_e32 v13, v11, v9
	v_mul_f32_e32 v8, v14, v8
	v_mul_f32_e32 v9, v15, v9
	v_sub_f32_e32 v0, v12, v13
	v_add_f32_e32 v5, v8, v9
	v_cndmask_b32_e64 v0, v5, v0, s[8:9]

.LBB0_753:
	s_or_b64 exec, exec, s[0:1]
	v_readlane_b32 s0, v254, 28
	v_readlane_b32 s1, v254, 29
	s_lshl_b32 s18, s10, 2
	s_andn2_b64 vcc, exec, s[0:1]
	s_waitcnt lgkmcnt(0)
	s_barrier
	s_cbranch_vccnz .LBB0_769
	v_readlane_b32 s0, v254, 30
	v_mov_b32_e32 v2, s27
	v_cmp_le_i32_e32 vcc, s18, v21
	v_mov_b32_e32 v3, s0
	v_readlane_b32 s0, v254, 31
	s_nop 1
	v_mov_b32_e32 v4, s0
	v_readlane_b32 s0, v254, 32
	s_nop 1
	v_mov_b32_e32 v5, s0
	v_readlane_b32 s0, v254, 33
	ds_read2_b32 v[8:9], v2 offset1:1
	ds_read2_b32 v[6:7], v3 offset1:1
	ds_read2_b32 v[2:3], v4 offset1:1
	ds_read2_b32 v[4:5], v5 offset1:1
	v_mov_b32_e32 v10, s0
	v_readlane_b32 s0, v254, 34
	s_nop 1
	v_mov_b32_e32 v11, s0
	v_readlane_b32 s0, v254, 35
	s_nop 1
	v_mov_b32_e32 v16, s0
	v_readlane_b32 s0, v254, 36
	s_nop 1
	v_mov_b32_e32 v18, s0
	ds_read2_b32 v[12:13], v10 offset1:1
	ds_read2_b32 v[14:15], v11 offset1:1
	ds_read2_b32 v[16:17], v16 offset1:1
	ds_read2_b32 v[10:11], v18 offset1:1
	s_lshl_b32 s0, s8, 7
	s_ashr_i32 s1, s0, 31
	s_lshl_b64 s[0:1], s[0:1], 2
	s_add_u32 s0, s30, s0
	s_addc_u32 s1, s31, s1
	s_add_u32 s8, s0, 0x210000
	s_addc_u32 s9, s1, 0
	s_add_i32 s12, s18, 4
	s_and_saveexec_b64 s[10:11], vcc
	s_xor_b64 s[10:11], exec, s[10:11]
	v_cmp_gt_i32_e64 s[0:1], s12, v21
	s_or_saveexec_b64 s[10:11], s[10:11]
	s_waitcnt lgkmcnt(7)
	v_max_f32_e32 v9, v9, v9
	v_max_f32_e32 v8, v8, v8
	s_waitcnt lgkmcnt(6)
	v_max_f32_e32 v7, v7, v7
	v_max_f32_e32 v6, v6, v6
	v_max_f32_e32 v8, v8, v9
	v_max_f32_e32 v6, v6, v7
	s_waitcnt lgkmcnt(5)
	v_max3_f32 v2, v8, v2, v3
	s_waitcnt lgkmcnt(4)
	v_max3_f32 v3, v6, v4, v5
	s_waitcnt lgkmcnt(3)
	v_max3_f32 v2, v2, v12, v13
	s_waitcnt lgkmcnt(2)
	v_max3_f32 v3, v3, v14, v15
	s_waitcnt lgkmcnt(1)
	v_max3_f32 v4, v2, v16, v17
	s_waitcnt lgkmcnt(0)
	v_max3_f32 v2, v3, v10, v11
	s_xor_b64 exec, exec, s[10:11]
	s_cbranch_execz .LBB0_758
	v_lshlrev_b32_e32 v3, 2, v21
	v_lshlrev_b32_e32 v5, 8, v21
	global_load_dword v6, v3, s[8:9]
	s_nop 0
	global_load_dword v3, v5, s[4:5] offset:252
	v_lshrrev_b32_e32 v5, 1, v21
	v_and_b32_e32 v5, 28, v5
	v_add_u32_e32 v5, s28, v5
	ds_read_b32 v7, v5
	s_mov_b32 s13, 0xc2400000
	s_andn2_b64 s[0:1], s[0:1], exec
	s_waitcnt vmcnt(1)
	v_mul_f32_e32 v6, v4, v6
	s_waitcnt vmcnt(0) lgkmcnt(0)
	v_add_f32_e32 v6, v2, v6
	v_add_f32_e32 v7, v3, v7
	s_nop 0
	v_sub_f32_e32 v3, v6, v7
	v_cmp_ngt_f32_e32 vcc, s13, v3
	s_and_b64 s[20:21], vcc, exec
	s_or_b64 s[0:1], s[0:1], s[20:21]

.LBB0_760:
	s_or_b64 exec, exec, s[10:11]
	v_or_b32_e32 v7, 64, v21
	v_cmp_le_i32_e64 s[0:1], s18, v7
	s_and_saveexec_b64 s[20:21], s[0:1]
	s_xor_b64 s[0:1], exec, s[20:21]
	v_cmp_gt_i32_e64 s[10:11], s12, v7
	s_andn2_saveexec_b64 s[12:13], s[0:1]
	s_cbranch_execz .LBB0_764
	v_lshlrev_b32_e32 v3, 2, v21
	v_lshlrev_b32_e32 v8, 8, v7
	global_load_dword v10, v3, s[8:9] offset:256
	s_nop 0
	global_load_dword v3, v8, s[4:5] offset:252
	v_lshrrev_b32_e32 v8, 1, v7
	v_and_b32_e32 v8, 60, v8
	v_add_u32_e32 v8, s28, v8
	ds_read_b32 v9, v8
	s_mov_b32 s0, 0xc2400000
	s_andn2_b64 s[8:9], s[10:11], exec
	s_waitcnt vmcnt(1)
	v_mul_f32_e32 v8, v4, v10
	s_waitcnt vmcnt(0) lgkmcnt(0)
	v_add_f32_e32 v2, v2, v8
	v_add_f32_e32 v3, v3, v9
	s_nop 0
	v_sub_f32_e32 v2, v2, v3
	v_cmp_ngt_f32_e64 s[0:1], s0, v2
	s_and_b64 s[0:1], s[0:1], exec
	s_or_b64 s[10:11], s[8:9], s[0:1]

.LBB0_788:
	s_waitcnt lgkmcnt(0)
	s_barrier
	s_add_i32 s13, s13, 2
	s_add_i32 s19, s19, 8
	v_add_f32_e32 v0, v84, v85
	s_cmp_ge_i32 s21, s12
	v_add_f32_e32 v86, v176, v0
	s_mov_b64 s[8:9], 0
	s_cselect_b64 s[10:11], -1, 0
	v_cmp_lt_f32_e32 vcc, 0x4b800000, v0
	s_cbranch_vccz .Lfox_noresc2
	s_nop 13
	v_log_f32_e32 v2, v0
	s_nop 0
	v_max_f32_e32 v2, 0, v2
	v_exp_f32_e64 v84, -v2
	v_sub_f32_e32 v4, v4, v2
	v_sub_f32_e32 v5, v5, v2
	v_sub_f32_e32 v6, v6, v2
	v_sub_f32_e32 v7, v7, v2
	v_sub_f32_e32 v8, v8, v2
	v_sub_f32_e32 v9, v9, v2
	v_sub_f32_e32 v10, v10, v2
	v_sub_f32_e32 v11, v11, v2
	v_sub_f32_e32 v12, v12, v2
	v_sub_f32_e32 v13, v13, v2
	v_sub_f32_e32 v14, v14, v2
	v_sub_f32_e32 v15, v15, v2
	v_sub_f32_e32 v16, v16, v2
	v_sub_f32_e32 v17, v17, v2
	v_sub_f32_e32 v18, v18, v2
	v_sub_f32_e32 v19, v19, v2
	v_mul_f32_e32 v86, v86, v84
	v_mul_f32_e32 v20, v20, v84
	v_mul_f32_e32 v21, v21, v84
	v_mul_f32_e32 v22, v22, v84
	v_mul_f32_e32 v23, v23, v84
	v_mul_f32_e32 v24, v24, v84
	v_mul_f32_e32 v25, v25, v84
	v_mul_f32_e32 v26, v26, v84
	v_mul_f32_e32 v27, v27, v84
	v_mul_f32_e32 v28, v28, v84
	v_mul_f32_e32 v29, v29, v84
	v_mul_f32_e32 v30, v30, v84
	v_mul_f32_e32 v31, v31, v84
	v_mul_f32_e32 v32, v32, v84
	v_mul_f32_e32 v33, v33, v84
	v_mul_f32_e32 v34, v34, v84
	v_mul_f32_e32 v35, v35, v84
	v_mul_f32_e32 v36, v36, v84
	v_mul_f32_e32 v37, v37, v84
	v_mul_f32_e32 v38, v38, v84
	v_mul_f32_e32 v39, v39, v84
	v_mul_f32_e32 v40, v40, v84
	v_mul_f32_e32 v41, v41, v84
	v_mul_f32_e32 v42, v42, v84
	v_mul_f32_e32 v43, v43, v84
	v_mul_f32_e32 v44, v44, v84
	v_mul_f32_e32 v45, v45, v84
	v_mul_f32_e32 v46, v46, v84
	v_mul_f32_e32 v47, v47, v84
	v_mul_f32_e32 v48, v48, v84
	v_mul_f32_e32 v49, v49, v84
	v_mul_f32_e32 v50, v50, v84
	v_mul_f32_e32 v51, v51, v84
	s_nop 1

.LBB0_802:
	s_waitcnt lgkmcnt(0)
	s_barrier
	v_add_f32_e32 v0, v84, v85
	s_add_i32 s10, s13, -3
	v_add_f32_e32 v175, v86, v0
	v_cmp_lt_f32_e32 vcc, 0x4b800000, v0
	s_cbranch_vccz .Lfox_noresc1
	s_nop 13
	v_log_f32_e32 v2, v0
	s_nop 0
	v_max_f32_e32 v2, 0, v2
	v_exp_f32_e64 v84, -v2
	v_sub_f32_e32 v4, v4, v2
	v_sub_f32_e32 v5, v5, v2
	v_sub_f32_e32 v6, v6, v2
	v_sub_f32_e32 v7, v7, v2
	v_sub_f32_e32 v8, v8, v2
	v_sub_f32_e32 v9, v9, v2
	v_sub_f32_e32 v10, v10, v2
	v_sub_f32_e32 v11, v11, v2
	v_sub_f32_e32 v12, v12, v2
	v_sub_f32_e32 v13, v13, v2
	v_sub_f32_e32 v14, v14, v2
	v_sub_f32_e32 v15, v15, v2
	v_sub_f32_e32 v16, v16, v2
	v_sub_f32_e32 v17, v17, v2
	v_sub_f32_e32 v18, v18, v2
	v_sub_f32_e32 v19, v19, v2
	v_mul_f32_e32 v175, v175, v84
	v_mul_f32_e32 v20, v20, v84
	v_mul_f32_e32 v21, v21, v84
	v_mul_f32_e32 v22, v22, v84
	v_mul_f32_e32 v23, v23, v84
	v_mul_f32_e32 v24, v24, v84
	v_mul_f32_e32 v25, v25, v84
	v_mul_f32_e32 v26, v26, v84
	v_mul_f32_e32 v27, v27, v84
	v_mul_f32_e32 v28, v28, v84
	v_mul_f32_e32 v29, v29, v84
	v_mul_f32_e32 v30, v30, v84
	v_mul_f32_e32 v31, v31, v84
	v_mul_f32_e32 v32, v32, v84
	v_mul_f32_e32 v33, v33, v84
	v_mul_f32_e32 v34, v34, v84
	v_mul_f32_e32 v35, v35, v84
	v_mul_f32_e32 v36, v36, v84
	v_mul_f32_e32 v37, v37, v84
	v_mul_f32_e32 v38, v38, v84
	v_mul_f32_e32 v39, v39, v84
	v_mul_f32_e32 v40, v40, v84
	v_mul_f32_e32 v41, v41, v84
	v_mul_f32_e32 v42, v42, v84
	v_mul_f32_e32 v43, v43, v84
	v_mul_f32_e32 v44, v44, v84
	v_mul_f32_e32 v45, v45, v84
	v_mul_f32_e32 v46, v46, v84
	v_mul_f32_e32 v47, v47, v84
	v_mul_f32_e32 v48, v48, v84
	v_mul_f32_e32 v49, v49, v84
	v_mul_f32_e32 v50, v50, v84
	v_mul_f32_e32 v51, v51, v84
	s_nop 1

.LBB0_823:
	s_or_b64 exec, exec, s[0:1]
	ds_read_b128 v[2:5], v215 offset:56064
	ds_read_b128 v[6:9], v178 offset:32768
	ds_read_b128 v[10:13], v215 offset:64256
	ds_read_b128 v[32:35], v178 offset:16384
	v_readlane_b32 s0, v254, 51
	s_waitcnt lgkmcnt(3)
	v_fma_f32 v36, v16, v0, v2
	v_fma_f32 v37, v17, v0, v3
	v_fma_f32 v18, v18, v0, v4
	v_fma_f32 v19, v19, v0, v5
	ds_read_b128 v[2:5], v178 offset:24576
	s_waitcnt lgkmcnt(3)
	v_fma_f32 v38, v48, v0, v6
	v_fma_f32 v39, v49, v0, v7
	ds_read_b128 v[14:17], v214
	v_fma_f32 v40, v50, v0, v8
	v_fma_f32 v41, v51, v0, v9
	s_waitcnt lgkmcnt(3)
	v_fma_f32 v20, v20, v0, v10
	v_fma_f32 v21, v21, v0, v11
	ds_read_b128 v[6:9], v213
	v_fma_f32 v22, v22, v0, v12
	v_fma_f32 v23, v23, v0, v13
	ds_read_b128 v[10:13], v179
	s_waitcnt lgkmcnt(3)
	v_fma_f32 v2, v28, v0, v2
	v_fma_f32 v3, v29, v0, v3
	v_lshlrev_b64 v[28:29], 11, v[166:167]
	v_readlane_b32 s1, v254, 52
	s_waitcnt lgkmcnt(2)
	v_fma_f32 v14, v52, v0, v14
	v_fma_f32 v15, v53, v0, v15
	v_fma_f32 v16, v54, v0, v16
	v_fma_f32 v17, v55, v0, v17
	v_fma_f32 v24, v24, v0, v32
	v_fma_f32 v25, v25, v0, v33
	s_waitcnt lgkmcnt(1)
	v_fma_f32 v6, v56, v0, v6
	v_fma_f32 v7, v57, v0, v7
	v_fma_f32 v26, v26, v0, v34
	v_fma_f32 v27, v27, v0, v35
	v_fma_f32 v8, v58, v0, v8
	v_fma_f32 v9, v59, v0, v9
	s_waitcnt lgkmcnt(0)
	v_fma_f32 v10, v60, v0, v10
	v_fma_f32 v11, v61, v0, v11
	v_fma_f32 v4, v30, v0, v4
	v_fma_f32 v5, v31, v0, v5
	v_fma_f32 v12, v62, v0, v12
	v_fma_f32 v13, v63, v0, v13
	v_lshl_add_u64 v[28:29], s[0:1], 0, v[28:29]
	v_lshlrev_b32_e32 v0, 1, v169
	v_lshl_add_u64 v[28:29], v[28:29], 0, v[0:1]
	v_lshlrev_b32_e32 v0, 5, v204
	v_lshl_add_u64 v[28:29], v[28:29], 0, v[0:1]
	s_mov_b64 s[0:1], 0xbe00400
	v_lshl_add_u64 v[30:31], v[28:29], 0, s[0:1]
	v_cvt_pk_bf16_f32 v48, v36, v37
	v_cvt_pk_bf16_f32 v49, v18, v19
	v_cvt_pk_bf16_f32 v50, v24, v25
	v_cvt_pk_bf16_f32 v51, v26, v27
	v_cvt_pk_bf16_f32 v52, v20, v21
	v_cvt_pk_bf16_f32 v53, v22, v23
	v_cvt_pk_bf16_f32 v54, v2, v3
	v_cvt_pk_bf16_f32 v55, v4, v5
	v_cvt_pk_bf16_f32 v56, v38, v39
	v_cvt_pk_bf16_f32 v57, v40, v41
	v_cvt_pk_bf16_f32 v58, v6, v7
	v_cvt_pk_bf16_f32 v59, v8, v9
	v_cvt_pk_bf16_f32 v60, v14, v15
	v_cvt_pk_bf16_f32 v61, v16, v17
	v_cvt_pk_bf16_f32 v62, v10, v11
	v_cvt_pk_bf16_f32 v63, v12, v13
	v_readlane_b32 s2, v254, 56
	v_readlane_b32 s3, v254, 57
	s_mov_b64 s[0:1], 0
	s_nop 0
	v_permlane32_swap_b32_e32 v48, v50
	v_permlane32_swap_b32_e32 v49, v51
	v_permlane32_swap_b32_e32 v52, v54
	v_permlane32_swap_b32_e32 v53, v55
	v_permlane32_swap_b32_e32 v56, v58
	v_permlane32_swap_b32_e32 v57, v59
	v_permlane32_swap_b32_e32 v60, v62
	v_permlane32_swap_b32_e32 v61, v63
	s_and_b64 vcc, exec, s[2:3]
	global_store_dwordx4 v[30:31], v[48:51], off
	global_store_dwordx4 v[30:31], v[52:55], off offset:16
	global_store_dwordx4 v[30:31], v[56:59], off offset:64
	global_store_dwordx4 v[30:31], v[60:63], off offset:80
	s_barrier
	s_cbranch_vccnz .LBB0_744

.LBB0_937:
	s_mov_b64 s[0:1], 0x2610
	v_lshl_add_u64 v[172:173], v[34:35], 0, s[0:1]
	s_waitcnt vmcnt(0)
	v_lshlrev_b32_e32 v34, 16, v36
	v_mul_f32_e32 v34, 0xbfb8aa3b, v34
	v_exp_f32_e32 v34, v34
	v_add_u32_e32 v215, s33, v37
	s_mov_b32 s87, s81
	v_add_u32_e32 v178, 0xdb00, v215
	v_add_f32_e32 v34, 1.0, v34
	v_div_scale_f32 v35, s[0:1], v34, v34, 1.0
	v_rcp_f32_e32 v36, v35
	v_div_scale_f32 v38, vcc, 1.0, v34, 1.0
	v_readlane_b32 s0, v254, 28
	v_fma_f32 v39, -v35, v36, 1.0
	v_fmac_f32_e32 v36, v39, v36
	v_mul_f32_e32 v39, v38, v36
	v_fma_f32 v40, -v35, v39, v38
	v_fmac_f32_e32 v39, v40, v36
	v_fma_f32 v35, -v35, v39, v38
	v_div_fmas_f32 v35, v35, v36, v39
	v_div_fixup_f32 v34, v35, v34, 1.0
	v_readlane_b32 s1, v254, 29
	v_mul_f32_e32 v20, v20, v34
	v_mul_f32_e32 v21, v21, v34
	v_mul_f32_e32 v18, v18, v34
	v_mul_f32_e32 v19, v19, v34
	v_mul_f32_e32 v16, v16, v34
	v_mul_f32_e32 v17, v17, v34
	v_mul_f32_e32 v14, v14, v34
	v_mul_f32_e32 v15, v15, v34
	v_mul_f32_e32 v12, v12, v34
	v_mul_f32_e32 v13, v13, v34
	v_mul_f32_e32 v10, v10, v34
	v_mul_f32_e32 v11, v11, v34
	v_mul_f32_e32 v8, v8, v34
	v_mul_f32_e32 v9, v9, v34
	v_mul_f32_e32 v6, v6, v34
	v_mul_f32_e32 v7, v7, v34
	v_add_u32_e32 v214, 0x17b00, v215
	v_add_u32_e32 v213, 0x19b00, v215
	v_add_u32_e32 v179, 0x1bb00, v215
	s_and_b64 vcc, exec, s[0:1]
	v_mul_f32_e32 v32, v32, v34
	v_mul_f32_e32 v33, v33, v34
	v_mul_f32_e32 v30, v30, v34
	v_mul_f32_e32 v31, v31, v34
	v_mul_f32_e32 v28, v28, v34
	v_mul_f32_e32 v29, v29, v34
	v_mul_f32_e32 v26, v26, v34
	v_mul_f32_e32 v27, v27, v34
	v_mul_f32_e32 v24, v24, v34
	v_mul_f32_e32 v25, v25, v34
	v_mul_f32_e32 v22, v22, v34
	v_mul_f32_e32 v23, v23, v34
	v_mul_f32_e32 v4, v4, v34
	v_mul_f32_e32 v5, v5, v34
	v_mul_f32_e32 v2, v2, v34
	v_mul_f32_e32 v3, v3, v34
	s_waitcnt lgkmcnt(0)
	s_barrier
	ds_write_b128 v215, v[18:21] offset:56064
	ds_write_b128 v178, v[2:5] offset:32768
	ds_write_b128 v215, v[22:25] offset:64256
	ds_write_b128 v214, v[6:9]
	ds_write_b128 v178, v[26:29] offset:16384
	ds_write_b128 v213, v[10:13]
	ds_write_b128 v178, v[30:33] offset:24576
	ds_write_b128 v179, v[14:17]
	s_cbranch_vccz .LBB0_943
	v_lshl_add_u32 v4, v211, 4, s27
	ds_read2_b32 v[2:3], v4 offset1:1
	ds_read2_b32 v[4:5], v4 offset0:2 offset1:3
	v_cmp_gt_u32_e32 vcc, 32, v211
	s_waitcnt lgkmcnt(1)
	ds_bpermute_b32 v6, v198, v2
	s_waitcnt lgkmcnt(0)
	v_or_b32_e32 v2, v6, v2
	ds_bpermute_b32 v6, v198, v3
	s_waitcnt lgkmcnt(0)
	v_or_b32_e32 v3, v6, v3
	ds_bpermute_b32 v6, v198, v4
	s_waitcnt lgkmcnt(0)
	v_or_b32_e32 v4, v6, v4
	ds_bpermute_b32 v6, v198, v5
	s_waitcnt lgkmcnt(0)
	v_or_b32_e32 v5, v6, v5
	ds_bpermute_b32 v6, v199, v2
	s_waitcnt lgkmcnt(0)
	v_or_b32_e32 v2, v6, v2
	ds_bpermute_b32 v6, v199, v3
	s_waitcnt lgkmcnt(0)
	v_or_b32_e32 v3, v6, v3
	ds_bpermute_b32 v6, v199, v4
	s_waitcnt lgkmcnt(0)
	v_or_b32_e32 v4, v6, v4
	ds_bpermute_b32 v6, v199, v5
	s_waitcnt lgkmcnt(0)
	v_or_b32_e32 v5, v6, v5
	ds_bpermute_b32 v6, v200, v2
	s_waitcnt lgkmcnt(0)
	v_or_b32_e32 v2, v6, v2
	ds_bpermute_b32 v6, v200, v3
	s_waitcnt lgkmcnt(0)
	v_or_b32_e32 v3, v6, v3
	ds_bpermute_b32 v6, v200, v4
	s_waitcnt lgkmcnt(0)
	v_or_b32_e32 v4, v6, v4
	ds_bpermute_b32 v6, v200, v5
	s_waitcnt lgkmcnt(0)
	v_or_b32_e32 v5, v6, v5
	ds_bpermute_b32 v6, v201, v2
	s_waitcnt lgkmcnt(0)
	v_or_b32_e32 v2, v6, v2
	ds_bpermute_b32 v6, v201, v3
	s_waitcnt lgkmcnt(0)
	v_or_b32_e32 v3, v6, v3
	ds_bpermute_b32 v6, v201, v4
	s_waitcnt lgkmcnt(0)
	v_or_b32_e32 v4, v6, v4
	ds_bpermute_b32 v6, v201, v5
	s_waitcnt lgkmcnt(0)
	v_or_b32_e32 v5, v6, v5
	ds_bpermute_b32 v6, v202, v2
	s_waitcnt lgkmcnt(0)
	v_or_b32_e32 v2, v6, v2
	ds_bpermute_b32 v6, v202, v3
	s_waitcnt lgkmcnt(0)
	v_or_b32_e32 v3, v6, v3
	ds_bpermute_b32 v6, v202, v4
	s_waitcnt lgkmcnt(0)
	v_or_b32_e32 v4, v6, v4
	ds_bpermute_b32 v6, v202, v5
	s_waitcnt lgkmcnt(0)
	v_or_b32_e32 v5, v6, v5
	ds_bpermute_b32 v6, v203, v2
	s_waitcnt lgkmcnt(0)
	v_or_b32_e32 v2, v6, v2
	ds_bpermute_b32 v6, v203, v3
	s_waitcnt lgkmcnt(0)
	v_or_b32_e32 v3, v6, v3
	ds_bpermute_b32 v6, v203, v4
	v_cndmask_b32_e32 v2, v3, v2, vcc
	s_waitcnt lgkmcnt(0)
	v_or_b32_e32 v4, v6, v4
	ds_bpermute_b32 v6, v203, v5
	s_waitcnt lgkmcnt(0)
	v_or_b32_e32 v5, v6, v5
	v_cndmask_b32_e32 v3, v5, v4, vcc
	v_lshlrev_b32_e64 v4, v212, 1
	v_and_b32_e32 v2, v2, v4
	v_cmp_ne_u32_e64 s[0:1], 0, v2
	v_and_b32_e32 v2, v3, v4
	v_lshlrev_b64 v[4:5], v211, -1
	v_cmp_ne_u32_e32 vcc, 0, v2
	v_not_b32_e32 v2, v5
	v_not_b32_e32 v3, v4
	s_and_saveexec_b64 s[2:3], s[0:1]
	s_cbranch_execz .LBB0_1010
	v_and_b32_e32 v5, s0, v3
	v_and_b32_e32 v4, s1, v2
	v_bcnt_u32_b32 v5, v5, 0
	v_bcnt_u32_b32 v4, v4, v5
	v_lshl_add_u32 v4, v4, 2, s29
	ds_write_b32 v4, v211 offset:4
	s_or_b64 exec, exec, s[2:3]
	s_bcnt1_i32_b64 s4, s[0:1]
	s_and_saveexec_b64 s[0:1], vcc
	s_cbranch_execnz .LBB0_1011

.Lsel_nodiag_0b:
	v_add_u32_e32 v187, s81, v208
	ds_read_b128 v[124:127], v187 offset:9216
	ds_read_b128 v[144:147], v187 offset:13824
	ds_read_b128 v[148:151], v187 offset:9248
	v_exp_f32_e32 v80, v80
	v_exp_f32_e32 v81, v81
	v_exp_f32_e32 v82, v82
	v_exp_f32_e32 v83, v83
	s_waitcnt lgkmcnt(6)
	v_mfma_f32_32x32x16_bf16 v[238:253], v[108:111], v[128:131], v[2:17]
	ds_read_b128 v[108:111], v0 offset:64
	v_exp_f32_e32 v84, v84
	v_exp_f32_e32 v85, v85
	v_exp_f32_e32 v86, v86
	v_exp_f32_e32 v87, v87
	s_waitcnt lgkmcnt(6)
	v_mfma_f32_32x32x16_bf16 v[222:237], v[112:115], v[128:131], v[2:17]
	ds_read_b128 v[112:115], v0 offset:4672
	v_add_f32_e32 v164, 0, v80
	v_add_f32_e32 v165, 0, v81
	v_add_f32_e32 v164, v82, v164
	v_add_f32_e32 v165, v83, v165
	v_cvt_pk_bf16_f32 v80, v80, v81
	v_cvt_pk_bf16_f32 v81, v82, v83
	v_add_f32_e32 v164, v84, v164
	v_add_f32_e32 v165, v85, v165
	v_add_f32_e32 v164, v86, v164
	v_add_f32_e32 v165, v87, v165
	v_cvt_pk_bf16_f32 v82, v84, v85
	v_cvt_pk_bf16_f32 v83, v86, v87
	v_cndmask_b32_e64 v80, v80, 0, s[72:73]
	v_cndmask_b32_e64 v81, v81, 0, s[72:73]
	v_cndmask_b32_e64 v82, v82, 0, s[72:73]
	v_cndmask_b32_e64 v83, v83, 0, s[72:73]
	v_exp_f32_e32 v88, v88
	v_exp_f32_e32 v89, v89
	s_waitcnt lgkmcnt(4)
	v_mfma_f32_32x32x16_bf16 v[48:63], v[124:127], v[80:83], v[48:63]
	ds_read_b128 v[124:127], v187 offset:13856
	v_exp_f32_e32 v90, v90
	v_exp_f32_e32 v91, v91
	s_waitcnt lgkmcnt(4)
	v_mfma_f32_32x32x16_bf16 v[32:47], v[144:147], v[80:83], v[32:47]
	ds_read_b128 v[144:147], v187 offset:9280
	v_exp_f32_e32 v92, v92
	v_exp_f32_e32 v93, v93
	v_mfma_f32_32x32x16_bf16 v[238:253], v[116:119], v[132:135], v[238:253]
	ds_read_b128 v[116:119], v0 offset:96
	v_exp_f32_e32 v94, v94
	v_exp_f32_e32 v95, v95
	v_mfma_f32_32x32x16_bf16 v[222:237], v[120:123], v[132:135], v[222:237]
	ds_read_b128 v[120:123], v0 offset:4704
	v_add_f32_e32 v164, v88, v164
	v_add_f32_e32 v165, v89, v165
	v_add_f32_e32 v164, v90, v164
	v_add_f32_e32 v165, v91, v165
	v_cvt_pk_bf16_f32 v88, v88, v89
	v_cvt_pk_bf16_f32 v89, v90, v91
	v_add_f32_e32 v164, v92, v164
	v_add_f32_e32 v165, v93, v165
	v_add_f32_e32 v164, v94, v164
	v_add_f32_e32 v165, v95, v165
	v_cvt_pk_bf16_f32 v90, v92, v93
	v_cvt_pk_bf16_f32 v91, v94, v95
	v_cndmask_b32_e64 v88, v88, 0, s[72:73]
	v_cndmask_b32_e64 v89, v89, 0, s[72:73]
	v_cndmask_b32_e64 v90, v90, 0, s[72:73]
	v_cndmask_b32_e64 v91, v91, 0, s[72:73]
	v_exp_f32_e32 v64, v64
	v_exp_f32_e32 v65, v65
	s_waitcnt lgkmcnt(6)
	v_mfma_f32_32x32x16_bf16 v[48:63], v[148:151], v[88:91], v[48:63]
	ds_read_b128 v[148:151], v187 offset:13888
	v_exp_f32_e32 v66, v66
	v_exp_f32_e32 v67, v67
	s_waitcnt lgkmcnt(4)
	v_mfma_f32_32x32x16_bf16 v[32:47], v[124:127], v[88:91], v[32:47]
	ds_read_b128 v[124:127], v187 offset:9312
	v_exp_f32_e32 v68, v68
	v_exp_f32_e32 v69, v69
	v_mfma_f32_32x32x16_bf16 v[238:253], v[108:111], v[136:139], v[238:253]
	v_exp_f32_e32 v70, v70
	v_exp_f32_e32 v71, v71
	v_mfma_f32_32x32x16_bf16 v[222:237], v[112:115], v[136:139], v[222:237]
	v_add_f32_e32 v164, v64, v164
	v_add_f32_e32 v165, v65, v165
	v_add_f32_e32 v164, v66, v164
	v_add_f32_e32 v165, v67, v165
	v_cvt_pk_bf16_f32 v64, v64, v65
	v_cvt_pk_bf16_f32 v65, v66, v67
	v_add_f32_e32 v164, v68, v164
	v_add_f32_e32 v165, v69, v165
	v_add_f32_e32 v164, v70, v164
	v_add_f32_e32 v165, v71, v165
	v_cvt_pk_bf16_f32 v66, v68, v69
	v_cvt_pk_bf16_f32 v67, v70, v71
	v_cndmask_b32_e64 v64, v64, 0, s[72:73]
	v_cndmask_b32_e64 v65, v65, 0, s[72:73]
	v_cndmask_b32_e64 v66, v66, 0, s[72:73]
	v_cndmask_b32_e64 v67, v67, 0, s[72:73]
	v_exp_f32_e32 v72, v72
	v_exp_f32_e32 v73, v73
	s_waitcnt lgkmcnt(4)
	v_mfma_f32_32x32x16_bf16 v[48:63], v[144:147], v[64:67], v[48:63]
	ds_read_b128 v[144:147], v187 offset:13920
	v_exp_f32_e32 v74, v74
	v_exp_f32_e32 v75, v75
	s_waitcnt lgkmcnt(2)
	v_mfma_f32_32x32x16_bf16 v[32:47], v[148:151], v[64:67], v[32:47]
	v_exp_f32_e32 v76, v76
	v_exp_f32_e32 v77, v77
	v_mfma_f32_32x32x16_bf16 v[238:253], v[116:119], v[140:143], v[238:253]
	v_exp_f32_e32 v78, v78
	v_exp_f32_e32 v79, v79
	v_mfma_f32_32x32x16_bf16 v[222:237], v[120:123], v[140:143], v[222:237]
	v_add_f32_e32 v164, v72, v164
	v_add_f32_e32 v165, v73, v165
	v_add_f32_e32 v164, v74, v164
	v_add_f32_e32 v165, v75, v165
	v_cvt_pk_bf16_f32 v72, v72, v73
	v_cvt_pk_bf16_f32 v73, v74, v75
	v_add_f32_e32 v164, v76, v164
	v_add_f32_e32 v165, v77, v165
	v_add_f32_e32 v164, v78, v164
	v_add_f32_e32 v165, v79, v165
	v_cvt_pk_bf16_f32 v74, v76, v77
	v_cvt_pk_bf16_f32 v75, v78, v79
	v_cndmask_b32_e64 v72, v72, 0, s[72:73]
	v_cndmask_b32_e64 v73, v73, 0, s[72:73]
	v_cndmask_b32_e64 v74, v74, 0, s[72:73]
	v_cndmask_b32_e64 v75, v75, 0, s[72:73]
	s_nop 1
	s_waitcnt lgkmcnt(1)
	v_mfma_f32_32x32x16_bf16 v[48:63], v[124:127], v[72:75], v[48:63]
	s_waitcnt lgkmcnt(0)
	v_mfma_f32_32x32x16_bf16 v[32:47], v[144:147], v[72:75], v[32:47]
	v_add_f32_e32 v164, v164, v165
	v_cndmask_b32_e64 v164, v164, 0, s[72:73]
	v_add_f32_e32 v106, v106, v164
	v_cmp_lt_f32_e32 vcc, 0x43800000, v164
	s_cbranch_vccz .Lsel_noresc_0b
	s_nop 15
	s_nop 15
	v_mov_b32_e32 v107, v164
	s_nop 1
	v_permlane32_swap_b32_e32 v164, v107
	v_add_f32_e32 v164, v164, v107
	v_log_f32_e32 v160, v164
	s_nop 0
	v_max_f32_e32 v160, 0, v160
	v_exp_f32_e64 v162, -v160
	v_sub_f32_e32 v2, v2, v160
	v_sub_f32_e32 v3, v3, v160
	v_sub_f32_e32 v4, v4, v160
	v_sub_f32_e32 v5, v5, v160
	v_sub_f32_e32 v6, v6, v160
	v_sub_f32_e32 v7, v7, v160
	v_sub_f32_e32 v8, v8, v160
	v_sub_f32_e32 v9, v9, v160
	v_sub_f32_e32 v10, v10, v160
	v_sub_f32_e32 v11, v11, v160
	v_sub_f32_e32 v12, v12, v160
	v_sub_f32_e32 v13, v13, v160
	v_sub_f32_e32 v14, v14, v160
	v_sub_f32_e32 v15, v15, v160
	v_sub_f32_e32 v16, v16, v160
	v_sub_f32_e32 v17, v17, v160
	v_mul_f32_e32 v106, v106, v162
	v_mul_f32_e32 v48, v48, v162
	v_mul_f32_e32 v49, v49, v162
	v_mul_f32_e32 v32, v32, v162
	v_mul_f32_e32 v33, v33, v162
	v_mul_f32_e32 v50, v50, v162
	v_mul_f32_e32 v51, v51, v162
	v_mul_f32_e32 v34, v34, v162
	v_mul_f32_e32 v35, v35, v162
	v_mul_f32_e32 v52, v52, v162
	v_mul_f32_e32 v53, v53, v162
	v_mul_f32_e32 v36, v36, v162
	v_mul_f32_e32 v37, v37, v162
	v_mul_f32_e32 v54, v54, v162
	v_mul_f32_e32 v55, v55, v162
	v_mul_f32_e32 v38, v38, v162
	v_mul_f32_e32 v39, v39, v162
	v_mul_f32_e32 v56, v56, v162
	v_mul_f32_e32 v57, v57, v162
	v_mul_f32_e32 v40, v40, v162
	v_mul_f32_e32 v41, v41, v162
	v_mul_f32_e32 v58, v58, v162
	v_mul_f32_e32 v59, v59, v162
	v_mul_f32_e32 v42, v42, v162
	v_mul_f32_e32 v43, v43, v162
	v_mul_f32_e32 v60, v60, v162
	v_mul_f32_e32 v61, v61, v162
	v_mul_f32_e32 v44, v44, v162
	v_mul_f32_e32 v45, v45, v162
	v_mul_f32_e32 v62, v62, v162
	v_mul_f32_e32 v63, v63, v162
	v_mul_f32_e32 v46, v46, v162
	v_mul_f32_e32 v47, v47, v162
	v_pk_add_f32 v[238:239], v[238:239], v[160:161] op_sel_hi:[1,0] neg_lo:[0,1] neg_hi:[0,1]
	v_pk_add_f32 v[222:223], v[222:223], v[160:161] op_sel_hi:[1,0] neg_lo:[0,1] neg_hi:[0,1]
	v_pk_add_f32 v[240:241], v[240:241], v[160:161] op_sel_hi:[1,0] neg_lo:[0,1] neg_hi:[0,1]
	v_pk_add_f32 v[224:225], v[224:225], v[160:161] op_sel_hi:[1,0] neg_lo:[0,1] neg_hi:[0,1]
	v_pk_add_f32 v[242:243], v[242:243], v[160:161] op_sel_hi:[1,0] neg_lo:[0,1] neg_hi:[0,1]
	v_pk_add_f32 v[226:227], v[226:227], v[160:161] op_sel_hi:[1,0] neg_lo:[0,1] neg_hi:[0,1]
	v_pk_add_f32 v[244:245], v[244:245], v[160:161] op_sel_hi:[1,0] neg_lo:[0,1] neg_hi:[0,1]
	v_pk_add_f32 v[228:229], v[228:229], v[160:161] op_sel_hi:[1,0] neg_lo:[0,1] neg_hi:[0,1]
	v_pk_add_f32 v[246:247], v[246:247], v[160:161] op_sel_hi:[1,0] neg_lo:[0,1] neg_hi:[0,1]
	v_pk_add_f32 v[230:231], v[230:231], v[160:161] op_sel_hi:[1,0] neg_lo:[0,1] neg_hi:[0,1]
	v_pk_add_f32 v[248:249], v[248:249], v[160:161] op_sel_hi:[1,0] neg_lo:[0,1] neg_hi:[0,1]
	v_pk_add_f32 v[232:233], v[232:233], v[160:161] op_sel_hi:[1,0] neg_lo:[0,1] neg_hi:[0,1]
	v_pk_add_f32 v[250:251], v[250:251], v[160:161] op_sel_hi:[1,0] neg_lo:[0,1] neg_hi:[0,1]
	v_pk_add_f32 v[234:235], v[234:235], v[160:161] op_sel_hi:[1,0] neg_lo:[0,1] neg_hi:[0,1]
	v_pk_add_f32 v[252:253], v[252:253], v[160:161] op_sel_hi:[1,0] neg_lo:[0,1] neg_hi:[0,1]
	v_pk_add_f32 v[236:237], v[236:237], v[160:161] op_sel_hi:[1,0] neg_lo:[0,1] neg_hi:[0,1]
	s_nop 1

.Lsel_nodiag_0c:
	v_add_u32_e32 v187, s81, v208
	ds_read_b128 v[124:127], v187 offset:9216
	ds_read_b128 v[144:147], v187 offset:13824
	ds_read_b128 v[148:151], v187 offset:9248
	v_exp_f32_e32 v80, v80
	v_exp_f32_e32 v81, v81
	v_exp_f32_e32 v82, v82
	v_exp_f32_e32 v83, v83
	v_exp_f32_e32 v84, v84
	v_exp_f32_e32 v85, v85
	v_exp_f32_e32 v86, v86
	v_exp_f32_e32 v87, v87
	v_add_f32_e32 v164, 0, v80
	v_add_f32_e32 v165, 0, v81
	v_add_f32_e32 v164, v82, v164
	v_add_f32_e32 v165, v83, v165
	v_cvt_pk_bf16_f32 v80, v80, v81
	v_cvt_pk_bf16_f32 v81, v82, v83
	v_add_f32_e32 v164, v84, v164
	v_add_f32_e32 v165, v85, v165
	v_add_f32_e32 v164, v86, v164
	v_add_f32_e32 v165, v87, v165
	v_cvt_pk_bf16_f32 v82, v84, v85
	v_cvt_pk_bf16_f32 v83, v86, v87
	v_cndmask_b32_e64 v80, v80, 0, s[72:73]
	v_cndmask_b32_e64 v81, v81, 0, s[72:73]
	v_cndmask_b32_e64 v82, v82, 0, s[72:73]
	v_cndmask_b32_e64 v83, v83, 0, s[72:73]
	v_exp_f32_e32 v88, v88
	v_exp_f32_e32 v89, v89
	s_waitcnt lgkmcnt(2)
	v_mfma_f32_32x32x16_bf16 v[48:63], v[124:127], v[80:83], v[48:63]
	ds_read_b128 v[124:127], v187 offset:13856
	v_exp_f32_e32 v90, v90
	v_exp_f32_e32 v91, v91
	s_waitcnt lgkmcnt(2)
	v_mfma_f32_32x32x16_bf16 v[32:47], v[144:147], v[80:83], v[32:47]
	ds_read_b128 v[144:147], v187 offset:9280
	v_exp_f32_e32 v92, v92
	v_exp_f32_e32 v93, v93
	v_exp_f32_e32 v94, v94
	v_exp_f32_e32 v95, v95
	v_add_f32_e32 v164, v88, v164
	v_add_f32_e32 v165, v89, v165
	v_add_f32_e32 v164, v90, v164
	v_add_f32_e32 v165, v91, v165
	v_cvt_pk_bf16_f32 v88, v88, v89
	v_cvt_pk_bf16_f32 v89, v90, v91
	v_add_f32_e32 v164, v92, v164
	v_add_f32_e32 v165, v93, v165
	v_add_f32_e32 v164, v94, v164
	v_add_f32_e32 v165, v95, v165
	v_cvt_pk_bf16_f32 v90, v92, v93
	v_cvt_pk_bf16_f32 v91, v94, v95
	v_cndmask_b32_e64 v88, v88, 0, s[72:73]
	v_cndmask_b32_e64 v89, v89, 0, s[72:73]
	v_cndmask_b32_e64 v90, v90, 0, s[72:73]
	v_cndmask_b32_e64 v91, v91, 0, s[72:73]
	v_exp_f32_e32 v64, v64
	v_exp_f32_e32 v65, v65
	s_waitcnt lgkmcnt(2)
	v_mfma_f32_32x32x16_bf16 v[48:63], v[148:151], v[88:91], v[48:63]
	ds_read_b128 v[148:151], v187 offset:13888
	v_exp_f32_e32 v66, v66
	v_exp_f32_e32 v67, v67
	s_waitcnt lgkmcnt(2)
	v_mfma_f32_32x32x16_bf16 v[32:47], v[124:127], v[88:91], v[32:47]
	ds_read_b128 v[124:127], v187 offset:9312
	v_exp_f32_e32 v68, v68
	v_exp_f32_e32 v69, v69
	v_exp_f32_e32 v70, v70
	v_exp_f32_e32 v71, v71
	v_add_f32_e32 v164, v64, v164
	v_add_f32_e32 v165, v65, v165
	v_add_f32_e32 v164, v66, v164
	v_add_f32_e32 v165, v67, v165
	v_cvt_pk_bf16_f32 v64, v64, v65
	v_cvt_pk_bf16_f32 v65, v66, v67
	v_add_f32_e32 v164, v68, v164
	v_add_f32_e32 v165, v69, v165
	v_add_f32_e32 v164, v70, v164
	v_add_f32_e32 v165, v71, v165
	v_cvt_pk_bf16_f32 v66, v68, v69
	v_cvt_pk_bf16_f32 v67, v70, v71
	v_cndmask_b32_e64 v64, v64, 0, s[72:73]
	v_cndmask_b32_e64 v65, v65, 0, s[72:73]
	v_cndmask_b32_e64 v66, v66, 0, s[72:73]
	v_cndmask_b32_e64 v67, v67, 0, s[72:73]
	v_exp_f32_e32 v72, v72
	v_exp_f32_e32 v73, v73
	s_waitcnt lgkmcnt(2)
	v_mfma_f32_32x32x16_bf16 v[48:63], v[144:147], v[64:67], v[48:63]
	ds_read_b128 v[144:147], v187 offset:13920
	v_exp_f32_e32 v74, v74
	v_exp_f32_e32 v75, v75
	s_waitcnt lgkmcnt(2)
	v_mfma_f32_32x32x16_bf16 v[32:47], v[148:151], v[64:67], v[32:47]
	v_exp_f32_e32 v76, v76
	v_exp_f32_e32 v77, v77
	v_exp_f32_e32 v78, v78
	v_exp_f32_e32 v79, v79
	v_add_f32_e32 v164, v72, v164
	v_add_f32_e32 v165, v73, v165
	v_add_f32_e32 v164, v74, v164
	v_add_f32_e32 v165, v75, v165
	v_cvt_pk_bf16_f32 v72, v72, v73
	v_cvt_pk_bf16_f32 v73, v74, v75
	v_add_f32_e32 v164, v76, v164
	v_add_f32_e32 v165, v77, v165
	v_add_f32_e32 v164, v78, v164
	v_add_f32_e32 v165, v79, v165
	v_cvt_pk_bf16_f32 v74, v76, v77
	v_cvt_pk_bf16_f32 v75, v78, v79
	v_cndmask_b32_e64 v72, v72, 0, s[72:73]
	v_cndmask_b32_e64 v73, v73, 0, s[72:73]
	v_cndmask_b32_e64 v74, v74, 0, s[72:73]
	v_cndmask_b32_e64 v75, v75, 0, s[72:73]
	s_nop 1
	s_waitcnt lgkmcnt(1)
	v_mfma_f32_32x32x16_bf16 v[48:63], v[124:127], v[72:75], v[48:63]
	s_waitcnt lgkmcnt(0)
	v_mfma_f32_32x32x16_bf16 v[32:47], v[144:147], v[72:75], v[32:47]
	v_add_f32_e32 v164, v164, v165
	v_cndmask_b32_e64 v164, v164, 0, s[72:73]
	v_add_f32_e32 v106, v106, v164
	v_cmp_lt_f32_e32 vcc, 0x43800000, v164
	s_cbranch_vccz .Lsel_noresc_0c
	s_nop 15
	s_nop 15
	v_mov_b32_e32 v107, v164
	s_nop 1
	v_permlane32_swap_b32_e32 v164, v107
	v_add_f32_e32 v164, v164, v107
	v_log_f32_e32 v160, v164
	s_nop 0
	v_max_f32_e32 v160, 0, v160
	v_exp_f32_e64 v162, -v160
	v_sub_f32_e32 v2, v2, v160
	v_sub_f32_e32 v3, v3, v160
	v_sub_f32_e32 v4, v4, v160
	v_sub_f32_e32 v5, v5, v160
	v_sub_f32_e32 v6, v6, v160
	v_sub_f32_e32 v7, v7, v160
	v_sub_f32_e32 v8, v8, v160
	v_sub_f32_e32 v9, v9, v160
	v_sub_f32_e32 v10, v10, v160
	v_sub_f32_e32 v11, v11, v160
	v_sub_f32_e32 v12, v12, v160
	v_sub_f32_e32 v13, v13, v160
	v_sub_f32_e32 v14, v14, v160
	v_sub_f32_e32 v15, v15, v160
	v_sub_f32_e32 v16, v16, v160
	v_sub_f32_e32 v17, v17, v160
	v_mul_f32_e32 v106, v106, v162
	v_mul_f32_e32 v48, v48, v162
	v_mul_f32_e32 v49, v49, v162
	v_mul_f32_e32 v32, v32, v162
	v_mul_f32_e32 v33, v33, v162
	v_mul_f32_e32 v50, v50, v162
	v_mul_f32_e32 v51, v51, v162
	v_mul_f32_e32 v34, v34, v162
	v_mul_f32_e32 v35, v35, v162
	v_mul_f32_e32 v52, v52, v162
	v_mul_f32_e32 v53, v53, v162
	v_mul_f32_e32 v36, v36, v162
	v_mul_f32_e32 v37, v37, v162
	v_mul_f32_e32 v54, v54, v162
	v_mul_f32_e32 v55, v55, v162
	v_mul_f32_e32 v38, v38, v162
	v_mul_f32_e32 v39, v39, v162
	v_mul_f32_e32 v56, v56, v162
	v_mul_f32_e32 v57, v57, v162
	v_mul_f32_e32 v40, v40, v162
	v_mul_f32_e32 v41, v41, v162
	v_mul_f32_e32 v58, v58, v162
	v_mul_f32_e32 v59, v59, v162
	v_mul_f32_e32 v42, v42, v162
	v_mul_f32_e32 v43, v43, v162
	v_mul_f32_e32 v60, v60, v162
	v_mul_f32_e32 v61, v61, v162
	v_mul_f32_e32 v44, v44, v162
	v_mul_f32_e32 v45, v45, v162
	v_mul_f32_e32 v62, v62, v162
	v_mul_f32_e32 v63, v63, v162
	v_mul_f32_e32 v46, v46, v162
	v_mul_f32_e32 v47, v47, v162
	s_nop 1

.Lsel_nodiag_1b:
	v_add_u32_e32 v187, s81, v208
	ds_read_b128 v[124:127], v187 offset:9216
	ds_read_b128 v[144:147], v187 offset:13824
	ds_read_b128 v[148:151], v187 offset:9248
	v_exp_f32_e32 v238, v238
	v_exp_f32_e32 v239, v239
	v_exp_f32_e32 v240, v240
	v_exp_f32_e32 v241, v241
	s_waitcnt lgkmcnt(6)
	v_mfma_f32_32x32x16_bf16 v[80:95], v[108:111], v[128:131], v[2:17]
	ds_read_b128 v[108:111], v0 offset:64
	v_exp_f32_e32 v242, v242
	v_exp_f32_e32 v243, v243
	v_exp_f32_e32 v244, v244
	v_exp_f32_e32 v245, v245
	s_waitcnt lgkmcnt(6)
	v_mfma_f32_32x32x16_bf16 v[64:79], v[112:115], v[128:131], v[2:17]
	ds_read_b128 v[112:115], v0 offset:4672
	v_add_f32_e32 v164, 0, v238
	v_add_f32_e32 v165, 0, v239
	v_add_f32_e32 v164, v240, v164
	v_add_f32_e32 v165, v241, v165
	v_cvt_pk_bf16_f32 v238, v238, v239
	v_cvt_pk_bf16_f32 v239, v240, v241
	v_add_f32_e32 v164, v242, v164
	v_add_f32_e32 v165, v243, v165
	v_add_f32_e32 v164, v244, v164
	v_add_f32_e32 v165, v245, v165
	v_cvt_pk_bf16_f32 v240, v242, v243
	v_cvt_pk_bf16_f32 v241, v244, v245
	v_cndmask_b32_e64 v238, v238, 0, s[72:73]
	v_cndmask_b32_e64 v239, v239, 0, s[72:73]
	v_cndmask_b32_e64 v240, v240, 0, s[72:73]
	v_cndmask_b32_e64 v241, v241, 0, s[72:73]
	v_exp_f32_e32 v246, v246
	v_exp_f32_e32 v247, v247
	s_waitcnt lgkmcnt(4)
	v_mfma_f32_32x32x16_bf16 v[48:63], v[124:127], v[238:241], v[48:63]
	ds_read_b128 v[124:127], v187 offset:13856
	v_exp_f32_e32 v248, v248
	v_exp_f32_e32 v249, v249
	s_waitcnt lgkmcnt(4)
	v_mfma_f32_32x32x16_bf16 v[32:47], v[144:147], v[238:241], v[32:47]
	ds_read_b128 v[144:147], v187 offset:9280
	v_exp_f32_e32 v250, v250
	v_exp_f32_e32 v251, v251
	v_mfma_f32_32x32x16_bf16 v[80:95], v[116:119], v[132:135], v[80:95]
	ds_read_b128 v[116:119], v0 offset:96
	v_exp_f32_e32 v252, v252
	v_exp_f32_e32 v253, v253
	v_mfma_f32_32x32x16_bf16 v[64:79], v[120:123], v[132:135], v[64:79]
	ds_read_b128 v[120:123], v0 offset:4704
	v_add_f32_e32 v164, v246, v164
	v_add_f32_e32 v165, v247, v165
	v_add_f32_e32 v164, v248, v164
	v_add_f32_e32 v165, v249, v165
	v_cvt_pk_bf16_f32 v246, v246, v247
	v_cvt_pk_bf16_f32 v247, v248, v249
	v_add_f32_e32 v164, v250, v164
	v_add_f32_e32 v165, v251, v165
	v_add_f32_e32 v164, v252, v164
	v_add_f32_e32 v165, v253, v165
	v_cvt_pk_bf16_f32 v248, v250, v251
	v_cvt_pk_bf16_f32 v249, v252, v253
	v_cndmask_b32_e64 v246, v246, 0, s[72:73]
	v_cndmask_b32_e64 v247, v247, 0, s[72:73]
	v_cndmask_b32_e64 v248, v248, 0, s[72:73]
	v_cndmask_b32_e64 v249, v249, 0, s[72:73]
	v_exp_f32_e32 v222, v222
	v_exp_f32_e32 v223, v223
	s_waitcnt lgkmcnt(6)
	v_mfma_f32_32x32x16_bf16 v[48:63], v[148:151], v[246:249], v[48:63]
	ds_read_b128 v[148:151], v187 offset:13888
	v_exp_f32_e32 v224, v224
	v_exp_f32_e32 v225, v225
	s_waitcnt lgkmcnt(4)
	v_mfma_f32_32x32x16_bf16 v[32:47], v[124:127], v[246:249], v[32:47]
	ds_read_b128 v[124:127], v187 offset:9312
	v_exp_f32_e32 v226, v226
	v_exp_f32_e32 v227, v227
	v_mfma_f32_32x32x16_bf16 v[80:95], v[108:111], v[136:139], v[80:95]
	v_exp_f32_e32 v228, v228
	v_exp_f32_e32 v229, v229
	v_mfma_f32_32x32x16_bf16 v[64:79], v[112:115], v[136:139], v[64:79]
	v_add_f32_e32 v164, v222, v164
	v_add_f32_e32 v165, v223, v165
	v_add_f32_e32 v164, v224, v164
	v_add_f32_e32 v165, v225, v165
	v_cvt_pk_bf16_f32 v222, v222, v223
	v_cvt_pk_bf16_f32 v223, v224, v225
	v_add_f32_e32 v164, v226, v164
	v_add_f32_e32 v165, v227, v165
	v_add_f32_e32 v164, v228, v164
	v_add_f32_e32 v165, v229, v165
	v_cvt_pk_bf16_f32 v224, v226, v227
	v_cvt_pk_bf16_f32 v225, v228, v229
	v_cndmask_b32_e64 v222, v222, 0, s[72:73]
	v_cndmask_b32_e64 v223, v223, 0, s[72:73]
	v_cndmask_b32_e64 v224, v224, 0, s[72:73]
	v_cndmask_b32_e64 v225, v225, 0, s[72:73]
	v_exp_f32_e32 v230, v230
	v_exp_f32_e32 v231, v231
	s_waitcnt lgkmcnt(4)
	v_mfma_f32_32x32x16_bf16 v[48:63], v[144:147], v[222:225], v[48:63]
	ds_read_b128 v[144:147], v187 offset:13920
	v_exp_f32_e32 v232, v232
	v_exp_f32_e32 v233, v233
	s_waitcnt lgkmcnt(2)
	v_mfma_f32_32x32x16_bf16 v[32:47], v[148:151], v[222:225], v[32:47]
	v_exp_f32_e32 v234, v234
	v_exp_f32_e32 v235, v235
	v_mfma_f32_32x32x16_bf16 v[80:95], v[116:119], v[140:143], v[80:95]
	v_exp_f32_e32 v236, v236
	v_exp_f32_e32 v237, v237
	v_mfma_f32_32x32x16_bf16 v[64:79], v[120:123], v[140:143], v[64:79]
	v_add_f32_e32 v164, v230, v164
	v_add_f32_e32 v165, v231, v165
	v_add_f32_e32 v164, v232, v164
	v_add_f32_e32 v165, v233, v165
	v_cvt_pk_bf16_f32 v230, v230, v231
	v_cvt_pk_bf16_f32 v231, v232, v233
	v_add_f32_e32 v164, v234, v164
	v_add_f32_e32 v165, v235, v165
	v_add_f32_e32 v164, v236, v164
	v_add_f32_e32 v165, v237, v165
	v_cvt_pk_bf16_f32 v232, v234, v235
	v_cvt_pk_bf16_f32 v233, v236, v237
	v_cndmask_b32_e64 v230, v230, 0, s[72:73]
	v_cndmask_b32_e64 v231, v231, 0, s[72:73]
	v_cndmask_b32_e64 v232, v232, 0, s[72:73]
	v_cndmask_b32_e64 v233, v233, 0, s[72:73]
	s_nop 1
	s_waitcnt lgkmcnt(1)
	v_mfma_f32_32x32x16_bf16 v[48:63], v[124:127], v[230:233], v[48:63]
	s_waitcnt lgkmcnt(0)
	v_mfma_f32_32x32x16_bf16 v[32:47], v[144:147], v[230:233], v[32:47]
	v_add_f32_e32 v164, v164, v165
	v_cndmask_b32_e64 v164, v164, 0, s[72:73]
	v_add_f32_e32 v106, v106, v164
	v_cmp_lt_f32_e32 vcc, 0x43800000, v164
	s_cbranch_vccz .Lsel_noresc_1b
	s_nop 15
	s_nop 15
	v_mov_b32_e32 v107, v164
	s_nop 1
	v_permlane32_swap_b32_e32 v164, v107
	v_add_f32_e32 v164, v164, v107
	v_log_f32_e32 v160, v164
	s_nop 0
	v_max_f32_e32 v160, 0, v160
	v_exp_f32_e64 v162, -v160
	v_sub_f32_e32 v2, v2, v160
	v_sub_f32_e32 v3, v3, v160
	v_sub_f32_e32 v4, v4, v160
	v_sub_f32_e32 v5, v5, v160
	v_sub_f32_e32 v6, v6, v160
	v_sub_f32_e32 v7, v7, v160
	v_sub_f32_e32 v8, v8, v160
	v_sub_f32_e32 v9, v9, v160
	v_sub_f32_e32 v10, v10, v160
	v_sub_f32_e32 v11, v11, v160
	v_sub_f32_e32 v12, v12, v160
	v_sub_f32_e32 v13, v13, v160
	v_sub_f32_e32 v14, v14, v160
	v_sub_f32_e32 v15, v15, v160
	v_sub_f32_e32 v16, v16, v160
	v_sub_f32_e32 v17, v17, v160
	v_mul_f32_e32 v106, v106, v162
	v_mul_f32_e32 v48, v48, v162
	v_mul_f32_e32 v49, v49, v162
	v_mul_f32_e32 v32, v32, v162
	v_mul_f32_e32 v33, v33, v162
	v_mul_f32_e32 v50, v50, v162
	v_mul_f32_e32 v51, v51, v162
	v_mul_f32_e32 v34, v34, v162
	v_mul_f32_e32 v35, v35, v162
	v_mul_f32_e32 v52, v52, v162
	v_mul_f32_e32 v53, v53, v162
	v_mul_f32_e32 v36, v36, v162
	v_mul_f32_e32 v37, v37, v162
	v_mul_f32_e32 v54, v54, v162
	v_mul_f32_e32 v55, v55, v162
	v_mul_f32_e32 v38, v38, v162
	v_mul_f32_e32 v39, v39, v162
	v_mul_f32_e32 v56, v56, v162
	v_mul_f32_e32 v57, v57, v162
	v_mul_f32_e32 v40, v40, v162
	v_mul_f32_e32 v41, v41, v162
	v_mul_f32_e32 v58, v58, v162
	v_mul_f32_e32 v59, v59, v162
	v_mul_f32_e32 v42, v42, v162
	v_mul_f32_e32 v43, v43, v162
	v_mul_f32_e32 v60, v60, v162
	v_mul_f32_e32 v61, v61, v162
	v_mul_f32_e32 v44, v44, v162
	v_mul_f32_e32 v45, v45, v162
	v_mul_f32_e32 v62, v62, v162
	v_mul_f32_e32 v63, v63, v162
	v_mul_f32_e32 v46, v46, v162
	v_mul_f32_e32 v47, v47, v162
	v_pk_add_f32 v[80:81], v[80:81], v[160:161] op_sel_hi:[1,0] neg_lo:[0,1] neg_hi:[0,1]
	v_pk_add_f32 v[64:65], v[64:65], v[160:161] op_sel_hi:[1,0] neg_lo:[0,1] neg_hi:[0,1]
	v_pk_add_f32 v[82:83], v[82:83], v[160:161] op_sel_hi:[1,0] neg_lo:[0,1] neg_hi:[0,1]
	v_pk_add_f32 v[66:67], v[66:67], v[160:161] op_sel_hi:[1,0] neg_lo:[0,1] neg_hi:[0,1]
	v_pk_add_f32 v[84:85], v[84:85], v[160:161] op_sel_hi:[1,0] neg_lo:[0,1] neg_hi:[0,1]
	v_pk_add_f32 v[68:69], v[68:69], v[160:161] op_sel_hi:[1,0] neg_lo:[0,1] neg_hi:[0,1]
	v_pk_add_f32 v[86:87], v[86:87], v[160:161] op_sel_hi:[1,0] neg_lo:[0,1] neg_hi:[0,1]
	v_pk_add_f32 v[70:71], v[70:71], v[160:161] op_sel_hi:[1,0] neg_lo:[0,1] neg_hi:[0,1]
	v_pk_add_f32 v[88:89], v[88:89], v[160:161] op_sel_hi:[1,0] neg_lo:[0,1] neg_hi:[0,1]
	v_pk_add_f32 v[72:73], v[72:73], v[160:161] op_sel_hi:[1,0] neg_lo:[0,1] neg_hi:[0,1]
	v_pk_add_f32 v[90:91], v[90:91], v[160:161] op_sel_hi:[1,0] neg_lo:[0,1] neg_hi:[0,1]
	v_pk_add_f32 v[74:75], v[74:75], v[160:161] op_sel_hi:[1,0] neg_lo:[0,1] neg_hi:[0,1]
	v_pk_add_f32 v[92:93], v[92:93], v[160:161] op_sel_hi:[1,0] neg_lo:[0,1] neg_hi:[0,1]
	v_pk_add_f32 v[76:77], v[76:77], v[160:161] op_sel_hi:[1,0] neg_lo:[0,1] neg_hi:[0,1]
	v_pk_add_f32 v[94:95], v[94:95], v[160:161] op_sel_hi:[1,0] neg_lo:[0,1] neg_hi:[0,1]
	v_pk_add_f32 v[78:79], v[78:79], v[160:161] op_sel_hi:[1,0] neg_lo:[0,1] neg_hi:[0,1]
	s_nop 1

.Lsel_nodiag_1c:
	v_add_u32_e32 v187, s81, v208
	ds_read_b128 v[124:127], v187 offset:9216
	ds_read_b128 v[144:147], v187 offset:13824
	ds_read_b128 v[148:151], v187 offset:9248
	v_exp_f32_e32 v238, v238
	v_exp_f32_e32 v239, v239
	v_exp_f32_e32 v240, v240
	v_exp_f32_e32 v241, v241
	v_exp_f32_e32 v242, v242
	v_exp_f32_e32 v243, v243
	v_exp_f32_e32 v244, v244
	v_exp_f32_e32 v245, v245
	v_add_f32_e32 v164, 0, v238
	v_add_f32_e32 v165, 0, v239
	v_add_f32_e32 v164, v240, v164
	v_add_f32_e32 v165, v241, v165
	v_cvt_pk_bf16_f32 v238, v238, v239
	v_cvt_pk_bf16_f32 v239, v240, v241
	v_add_f32_e32 v164, v242, v164
	v_add_f32_e32 v165, v243, v165
	v_add_f32_e32 v164, v244, v164
	v_add_f32_e32 v165, v245, v165
	v_cvt_pk_bf16_f32 v240, v242, v243
	v_cvt_pk_bf16_f32 v241, v244, v245
	v_cndmask_b32_e64 v238, v238, 0, s[72:73]
	v_cndmask_b32_e64 v239, v239, 0, s[72:73]
	v_cndmask_b32_e64 v240, v240, 0, s[72:73]
	v_cndmask_b32_e64 v241, v241, 0, s[72:73]
	v_exp_f32_e32 v246, v246
	v_exp_f32_e32 v247, v247
	s_waitcnt lgkmcnt(2)
	v_mfma_f32_32x32x16_bf16 v[48:63], v[124:127], v[238:241], v[48:63]
	ds_read_b128 v[124:127], v187 offset:13856
	v_exp_f32_e32 v248, v248
	v_exp_f32_e32 v249, v249
	s_waitcnt lgkmcnt(2)
	v_mfma_f32_32x32x16_bf16 v[32:47], v[144:147], v[238:241], v[32:47]
	ds_read_b128 v[144:147], v187 offset:9280
	v_exp_f32_e32 v250, v250
	v_exp_f32_e32 v251, v251
	v_exp_f32_e32 v252, v252
	v_exp_f32_e32 v253, v253
	v_add_f32_e32 v164, v246, v164
	v_add_f32_e32 v165, v247, v165
	v_add_f32_e32 v164, v248, v164
	v_add_f32_e32 v165, v249, v165
	v_cvt_pk_bf16_f32 v246, v246, v247
	v_cvt_pk_bf16_f32 v247, v248, v249
	v_add_f32_e32 v164, v250, v164
	v_add_f32_e32 v165, v251, v165
	v_add_f32_e32 v164, v252, v164
	v_add_f32_e32 v165, v253, v165
	v_cvt_pk_bf16_f32 v248, v250, v251
	v_cvt_pk_bf16_f32 v249, v252, v253
	v_cndmask_b32_e64 v246, v246, 0, s[72:73]
	v_cndmask_b32_e64 v247, v247, 0, s[72:73]
	v_cndmask_b32_e64 v248, v248, 0, s[72:73]
	v_cndmask_b32_e64 v249, v249, 0, s[72:73]
	v_exp_f32_e32 v222, v222
	v_exp_f32_e32 v223, v223
	s_waitcnt lgkmcnt(2)
	v_mfma_f32_32x32x16_bf16 v[48:63], v[148:151], v[246:249], v[48:63]
	ds_read_b128 v[148:151], v187 offset:13888
	v_exp_f32_e32 v224, v224
	v_exp_f32_e32 v225, v225
	s_waitcnt lgkmcnt(2)
	v_mfma_f32_32x32x16_bf16 v[32:47], v[124:127], v[246:249], v[32:47]
	ds_read_b128 v[124:127], v187 offset:9312
	v_exp_f32_e32 v226, v226
	v_exp_f32_e32 v227, v227
	v_exp_f32_e32 v228, v228
	v_exp_f32_e32 v229, v229
	v_add_f32_e32 v164, v222, v164
	v_add_f32_e32 v165, v223, v165
	v_add_f32_e32 v164, v224, v164
	v_add_f32_e32 v165, v225, v165
	v_cvt_pk_bf16_f32 v222, v222, v223
	v_cvt_pk_bf16_f32 v223, v224, v225
	v_add_f32_e32 v164, v226, v164
	v_add_f32_e32 v165, v227, v165
	v_add_f32_e32 v164, v228, v164
	v_add_f32_e32 v165, v229, v165
	v_cvt_pk_bf16_f32 v224, v226, v227
	v_cvt_pk_bf16_f32 v225, v228, v229
	v_cndmask_b32_e64 v222, v222, 0, s[72:73]
	v_cndmask_b32_e64 v223, v223, 0, s[72:73]
	v_cndmask_b32_e64 v224, v224, 0, s[72:73]
	v_cndmask_b32_e64 v225, v225, 0, s[72:73]
	v_exp_f32_e32 v230, v230
	v_exp_f32_e32 v231, v231
	s_waitcnt lgkmcnt(2)
	v_mfma_f32_32x32x16_bf16 v[48:63], v[144:147], v[222:225], v[48:63]
	ds_read_b128 v[144:147], v187 offset:13920
	v_exp_f32_e32 v232, v232
	v_exp_f32_e32 v233, v233
	s_waitcnt lgkmcnt(2)
	v_mfma_f32_32x32x16_bf16 v[32:47], v[148:151], v[222:225], v[32:47]
	v_exp_f32_e32 v234, v234
	v_exp_f32_e32 v235, v235
	v_exp_f32_e32 v236, v236
	v_exp_f32_e32 v237, v237
	v_add_f32_e32 v164, v230, v164
	v_add_f32_e32 v165, v231, v165
	v_add_f32_e32 v164, v232, v164
	v_add_f32_e32 v165, v233, v165
	v_cvt_pk_bf16_f32 v230, v230, v231
	v_cvt_pk_bf16_f32 v231, v232, v233
	v_add_f32_e32 v164, v234, v164
	v_add_f32_e32 v165, v235, v165
	v_add_f32_e32 v164, v236, v164
	v_add_f32_e32 v165, v237, v165
	v_cvt_pk_bf16_f32 v232, v234, v235
	v_cvt_pk_bf16_f32 v233, v236, v237
	v_cndmask_b32_e64 v230, v230, 0, s[72:73]
	v_cndmask_b32_e64 v231, v231, 0, s[72:73]
	v_cndmask_b32_e64 v232, v232, 0, s[72:73]
	v_cndmask_b32_e64 v233, v233, 0, s[72:73]
	s_nop 1
	s_waitcnt lgkmcnt(1)
	v_mfma_f32_32x32x16_bf16 v[48:63], v[124:127], v[230:233], v[48:63]
	s_waitcnt lgkmcnt(0)
	v_mfma_f32_32x32x16_bf16 v[32:47], v[144:147], v[230:233], v[32:47]
	v_add_f32_e32 v164, v164, v165
	v_cndmask_b32_e64 v164, v164, 0, s[72:73]
	v_add_f32_e32 v106, v106, v164
	v_cmp_lt_f32_e32 vcc, 0x43800000, v164
	s_cbranch_vccz .Lsel_noresc_1c
	s_nop 15
	s_nop 15
	v_mov_b32_e32 v107, v164
	s_nop 1
	v_permlane32_swap_b32_e32 v164, v107
	v_add_f32_e32 v164, v164, v107
	v_log_f32_e32 v160, v164
	s_nop 0
	v_max_f32_e32 v160, 0, v160
	v_exp_f32_e64 v162, -v160
	v_sub_f32_e32 v2, v2, v160
	v_sub_f32_e32 v3, v3, v160
	v_sub_f32_e32 v4, v4, v160
	v_sub_f32_e32 v5, v5, v160
	v_sub_f32_e32 v6, v6, v160
	v_sub_f32_e32 v7, v7, v160
	v_sub_f32_e32 v8, v8, v160
	v_sub_f32_e32 v9, v9, v160
	v_sub_f32_e32 v10, v10, v160
	v_sub_f32_e32 v11, v11, v160
	v_sub_f32_e32 v12, v12, v160
	v_sub_f32_e32 v13, v13, v160
	v_sub_f32_e32 v14, v14, v160
	v_sub_f32_e32 v15, v15, v160
	v_sub_f32_e32 v16, v16, v160
	v_sub_f32_e32 v17, v17, v160
	v_mul_f32_e32 v106, v106, v162
	v_mul_f32_e32 v48, v48, v162
	v_mul_f32_e32 v49, v49, v162
	v_mul_f32_e32 v32, v32, v162
	v_mul_f32_e32 v33, v33, v162
	v_mul_f32_e32 v50, v50, v162
	v_mul_f32_e32 v51, v51, v162
	v_mul_f32_e32 v34, v34, v162
	v_mul_f32_e32 v35, v35, v162
	v_mul_f32_e32 v52, v52, v162
	v_mul_f32_e32 v53, v53, v162
	v_mul_f32_e32 v36, v36, v162
	v_mul_f32_e32 v37, v37, v162
	v_mul_f32_e32 v54, v54, v162
	v_mul_f32_e32 v55, v55, v162
	v_mul_f32_e32 v38, v38, v162
	v_mul_f32_e32 v39, v39, v162
	v_mul_f32_e32 v56, v56, v162
	v_mul_f32_e32 v57, v57, v162
	v_mul_f32_e32 v40, v40, v162
	v_mul_f32_e32 v41, v41, v162
	v_mul_f32_e32 v58, v58, v162
	v_mul_f32_e32 v59, v59, v162
	v_mul_f32_e32 v42, v42, v162
	v_mul_f32_e32 v43, v43, v162
	v_mul_f32_e32 v60, v60, v162
	v_mul_f32_e32 v61, v61, v162
	v_mul_f32_e32 v44, v44, v162
	v_mul_f32_e32 v45, v45, v162
	v_mul_f32_e32 v62, v62, v162
	v_mul_f32_e32 v63, v63, v162
	v_mul_f32_e32 v46, v46, v162
	v_mul_f32_e32 v47, v47, v162
	s_nop 1

.LBB0_981:
	s_or_b64 exec, exec, s[0:1]
	ds_read_b128 v[2:5], v215 offset:56064
	ds_read_b128 v[6:9], v178 offset:32768
	ds_read_b128 v[10:13], v215 offset:64256
	ds_read_b128 v[14:17], v214
	s_waitcnt vmcnt(1)
	ds_read_b128 v[18:21], v178 offset:16384
	s_waitcnt vmcnt(0)
	ds_read_b128 v[22:25], v213
	s_max_i32 s8, s84, 8
	s_add_i32 s7, s8, -8
	s_waitcnt lgkmcnt(0)
	v_fma_f32 v6, v32, v0, v6
	v_fma_f32 v7, v33, v0, v7
	v_fma_f32 v8, v34, v0, v8
	v_fma_f32 v9, v35, v0, v9
	ds_read_b128 v[26:29], v178 offset:24576
	ds_read_b128 v[32:35], v179
	v_fma_f32 v2, v48, v0, v2
	v_fma_f32 v3, v49, v0, v3
	v_fma_f32 v4, v50, v0, v4
	v_fma_f32 v5, v51, v0, v5
	v_fma_f32 v16, v38, v0, v16
	v_fma_f32 v17, v39, v0, v17
	v_fma_f32 v18, v56, v0, v18
	v_fma_f32 v19, v57, v0, v19
	v_fma_f32 v22, v40, v0, v22
	v_fma_f32 v23, v41, v0, v23
	v_fma_f32 v20, v58, v0, v20
	v_fma_f32 v21, v59, v0, v21
	v_fma_f32 v24, v42, v0, v24
	v_fma_f32 v25, v43, v0, v25
	s_waitcnt lgkmcnt(1)
	v_fma_f32 v26, v60, v0, v26
	v_fma_f32 v27, v61, v0, v27
	v_fma_f32 v28, v62, v0, v28
	v_fma_f32 v29, v63, v0, v29
	s_sub_i32 s6, s84, s7
	v_fma_f32 v10, v52, v0, v10
	v_fma_f32 v11, v53, v0, v11
	v_fma_f32 v14, v36, v0, v14
	v_fma_f32 v15, v37, v0, v15
	v_fma_f32 v12, v54, v0, v12
	v_fma_f32 v13, v55, v0, v13
	s_waitcnt lgkmcnt(0)
	v_fma_f32 v32, v44, v0, v32
	v_fma_f32 v33, v45, v0, v33
	v_fma_f32 v34, v46, v0, v34
	v_fma_f32 v35, v47, v0, v35
	ds_write_b128 v215, v[2:5] offset:56064
	ds_write_b128 v178, v[6:9] offset:32768
	ds_write_b128 v215, v[10:13] offset:64256
	ds_write_b128 v214, v[14:17]
	ds_write_b128 v178, v[18:21] offset:16384
	ds_write_b128 v213, v[22:25]
	ds_write_b128 v178, v[26:29] offset:24576
	ds_write_b128 v179, v[32:35]
	s_cmp_lt_i32 s6, 0
	v_mov_b32_e32 v30, 0
	v_mov_b32_e32 v29, 0
	v_mov_b32_e32 v28, 0
	v_mov_b32_e32 v27, 0
	v_mov_b32_e32 v26, 0
	v_mov_b32_e32 v25, 0
	v_mov_b32_e32 v24, 0
	v_mov_b32_e32 v23, 0
	v_mov_b32_e32 v22, 0
	v_mov_b32_e32 v21, 0
	v_mov_b32_e32 v20, 0
	v_mov_b32_e32 v19, 0
	v_mov_b32_e32 v18, 0
	v_mov_b32_e32 v17, 0
	v_mov_b32_e32 v16, 0
	v_mov_b32_e32 v63, 0
	v_mov_b32_e32 v62, 0
	v_mov_b32_e32 v61, 0
	v_mov_b32_e32 v60, 0
	v_mov_b32_e32 v59, 0
	v_mov_b32_e32 v58, 0
	v_mov_b32_e32 v57, 0
	v_mov_b32_e32 v56, 0
	v_mov_b32_e32 v55, 0
	v_mov_b32_e32 v54, 0
	v_mov_b32_e32 v53, 0
	v_mov_b32_e32 v52, 0
	v_mov_b32_e32 v51, 0
	v_mov_b32_e32 v50, 0
	v_mov_b32_e32 v49, 0
	v_mov_b32_e32 v48, 0
	v_mov_b32_e32 v96, 0
	s_cbranch_scc1 .LBB0_1016
	s_lshl_b32 s0, s94, 12
	s_and_b32 s0, s0, 0xffffe000
	s_mul_hi_i32 s1, s0, 0x2640
	s_mulk_i32 s0, 0x2640
	v_readlane_b32 s2, v254, 54
	v_readlane_b32 s3, v254, 55
	s_add_u32 s0, s2, s0
	s_addc_u32 s1, s3, s1
	s_lshl_b32 s2, s94, 7
	s_and_b32 s2, s2, 0x80
	s_add_u32 s2, s0, s2
	s_addc_u32 s3, s1, 0
	s_add_u32 s0, s2, 0x1400
	s_addc_u32 s1, s3, 0
	s_add_u32 s2, s2, 0x1500
	s_addc_u32 s3, s3, 0
	v_lshl_add_u32 v2, s7, 6, v100
	v_mov_b64_e32 v[4:5], s[0:1]
	v_mad_i64_i32 v[4:5], s[4:5], v2, s90, v[4:5]
	v_mov_b32_e32 v171, v1
	v_mov_b64_e32 v[6:7], s[2:3]
	v_lshl_add_u64 v[4:5], v[4:5], 0, v[170:171]
	v_mad_i64_i32 v[6:7], s[4:5], v2, s90, v[6:7]
	v_lshl_add_u64 v[6:7], v[6:7], 0, v[170:171]
	global_load_dwordx4 v[144:147], v[4:5], off
	global_load_dwordx4 v[148:151], v[6:7], off
	s_cmp_lg_u32 s84, s7
	s_cselect_b64 s[4:5], -1, 0
	s_cmp_eq_u32 s84, s7
	v_lshlrev_b32_e32 v0, 1, v102
	s_cbranch_scc1 .LBB0_984
	v_add_u32_e32 v3, 64, v2
	v_mov_b64_e32 v[4:5], s[0:1]
	v_mad_i64_i32 v[4:5], s[10:11], v3, s90, v[4:5]
	v_mov_b64_e32 v[6:7], s[2:3]
	v_lshl_add_u64 v[4:5], v[4:5], 0, v[0:1]
	v_mad_i64_i32 v[6:7], s[10:11], v3, s90, v[6:7]
	v_lshl_add_u64 v[6:7], v[6:7], 0, v[0:1]
	global_load_dwordx4 v[152:155], v[4:5], off
	global_load_dwordx4 v[156:159], v[6:7], off

.LBB0_997:
	v_add_f32_e32 v0, v2, v3
	s_waitcnt lgkmcnt(0)
	s_barrier
	v_mov_b32_e32 v2, v0
	v_add_f32_e32 v0, v96, v0
	v_cmp_lt_f32_e32 vcc, 0x4b800000, v2
	s_cbranch_vccz .Lwin_noresc1
	s_nop 13
	v_log_f32_e32 v5, v2
	s_nop 0
	v_max_f32_e32 v5, 0, v5
	v_exp_f32_e64 v4, -v5
	v_sub_f32_e32 v32, v32, v5
	v_sub_f32_e32 v33, v33, v5
	v_sub_f32_e32 v34, v34, v5
	v_sub_f32_e32 v35, v35, v5
	v_sub_f32_e32 v36, v36, v5
	v_sub_f32_e32 v37, v37, v5
	v_sub_f32_e32 v38, v38, v5
	v_sub_f32_e32 v39, v39, v5
	v_sub_f32_e32 v40, v40, v5
	v_sub_f32_e32 v41, v41, v5
	v_sub_f32_e32 v42, v42, v5
	v_sub_f32_e32 v43, v43, v5
	v_sub_f32_e32 v44, v44, v5
	v_sub_f32_e32 v45, v45, v5
	v_sub_f32_e32 v46, v46, v5
	v_sub_f32_e32 v47, v47, v5
	v_mul_f32_e32 v0, v0, v4
	v_mul_f32_e32 v80, v80, v4
	v_mul_f32_e32 v81, v81, v4
	v_mul_f32_e32 v82, v82, v4
	v_mul_f32_e32 v83, v83, v4
	v_mul_f32_e32 v84, v84, v4
	v_mul_f32_e32 v85, v85, v4
	v_mul_f32_e32 v86, v86, v4
	v_mul_f32_e32 v87, v87, v4
	v_mul_f32_e32 v88, v88, v4
	v_mul_f32_e32 v89, v89, v4
	v_mul_f32_e32 v90, v90, v4
	v_mul_f32_e32 v91, v91, v4
	v_mul_f32_e32 v92, v92, v4
	v_mul_f32_e32 v93, v93, v4
	v_mul_f32_e32 v94, v94, v4
	v_mul_f32_e32 v95, v95, v4
	v_mul_f32_e32 v64, v64, v4
	v_mul_f32_e32 v65, v65, v4
	v_mul_f32_e32 v66, v66, v4
	v_mul_f32_e32 v67, v67, v4
	v_mul_f32_e32 v68, v68, v4
	v_mul_f32_e32 v69, v69, v4
	v_mul_f32_e32 v70, v70, v4
	v_mul_f32_e32 v71, v71, v4
	v_mul_f32_e32 v72, v72, v4
	v_mul_f32_e32 v73, v73, v4
	v_mul_f32_e32 v74, v74, v4
	v_mul_f32_e32 v75, v75, v4
	v_mul_f32_e32 v76, v76, v4
	v_mul_f32_e32 v77, v77, v4
	v_mul_f32_e32 v78, v78, v4
	v_mul_f32_e32 v79, v79, v4
	s_nop 1

.LBB0_1007:
	s_waitcnt lgkmcnt(0)
	s_barrier
	s_add_i32 s15, s10, 2
	v_add_f32_e32 v2, v2, v3
	v_add_f32_e32 v96, v5, v2
	v_cmp_lt_f32_e32 vcc, 0x4b800000, v2
	s_cbranch_vccz .Lwin_noresc2
	s_nop 13
	v_log_f32_e32 v5, v2
	s_nop 0
	v_max_f32_e32 v5, 0, v5
	v_exp_f32_e64 v4, -v5
	v_sub_f32_e32 v32, v32, v5
	v_sub_f32_e32 v33, v33, v5
	v_sub_f32_e32 v34, v34, v5
	v_sub_f32_e32 v35, v35, v5
	v_sub_f32_e32 v36, v36, v5
	v_sub_f32_e32 v37, v37, v5
	v_sub_f32_e32 v38, v38, v5
	v_sub_f32_e32 v39, v39, v5
	v_sub_f32_e32 v40, v40, v5
	v_sub_f32_e32 v41, v41, v5
	v_sub_f32_e32 v42, v42, v5
	v_sub_f32_e32 v43, v43, v5
	v_sub_f32_e32 v44, v44, v5
	v_sub_f32_e32 v45, v45, v5
	v_sub_f32_e32 v46, v46, v5
	v_sub_f32_e32 v47, v47, v5
	v_mul_f32_e32 v96, v96, v4
	v_mul_f32_e32 v16, v16, v4
	v_mul_f32_e32 v17, v17, v4
	v_mul_f32_e32 v18, v18, v4
	v_mul_f32_e32 v19, v19, v4
	v_mul_f32_e32 v20, v20, v4
	v_mul_f32_e32 v21, v21, v4
	v_mul_f32_e32 v22, v22, v4
	v_mul_f32_e32 v23, v23, v4
	v_mul_f32_e32 v24, v24, v4
	v_mul_f32_e32 v25, v25, v4
	v_mul_f32_e32 v26, v26, v4
	v_mul_f32_e32 v27, v27, v4
	v_mul_f32_e32 v28, v28, v4
	v_mul_f32_e32 v29, v29, v4
	v_mul_f32_e32 v30, v30, v4
	v_mul_f32_e32 v31, v31, v4
	v_mul_f32_e32 v48, v48, v4
	v_mul_f32_e32 v49, v49, v4
	v_mul_f32_e32 v50, v50, v4
	v_mul_f32_e32 v51, v51, v4
	v_mul_f32_e32 v52, v52, v4
	v_mul_f32_e32 v53, v53, v4
	v_mul_f32_e32 v54, v54, v4
	v_mul_f32_e32 v55, v55, v4
	v_mul_f32_e32 v56, v56, v4
	v_mul_f32_e32 v57, v57, v4
	v_mul_f32_e32 v58, v58, v4
	v_mul_f32_e32 v59, v59, v4
	v_mul_f32_e32 v60, v60, v4
	v_mul_f32_e32 v61, v61, v4
	v_mul_f32_e32 v62, v62, v4
	v_mul_f32_e32 v63, v63, v4
	s_nop 1

.LBB0_1475:
	s_ashr_i32 s3, s2, 31
	s_lshl_b64 s[0:1], s[2:3], 6
	s_add_u32 s0, s4, s0
	s_addc_u32 s1, s5, s1
	global_load_dwordx4 v[100:103], v97, s[0:1] offset:48
	global_load_dwordx4 v[104:107], v97, s[0:1] offset:32
	global_load_dwordx4 v[108:111], v97, s[0:1] offset:16
	global_load_dwordx4 v[112:115], v97, s[0:1]
	s_lshl_b64 s[0:1], s[2:3], 12
	s_add_i32 s16, s7, s2
	s_cmpk_lt_i32 s16, 0x4000
	s_cselect_b32 s8, s16, s2
	s_ashr_i32 s9, s8, 31
	s_lshl_b64 s[10:11], s[8:9], 6
	s_add_u32 s22, s4, s10
	s_addc_u32 s23, s5, s11
	s_lshl_b64 s[24:25], s[8:9], 12
	s_add_i32 s12, s19, s2
	s_cmpk_lt_i32 s12, 0x4000
	s_cselect_b64 s[14:15], -1, 0
	s_and_b64 s[8:9], s[14:15], exec
	s_cselect_b32 s8, s12, s2
	s_ashr_i32 s9, s8, 31
	s_lshl_b64 s[10:11], s[8:9], 6
	s_add_u32 s26, s4, s10
	s_addc_u32 s27, s5, s11
	s_lshl_b64 s[28:29], s[8:9], 12
	s_add_i32 s8, s20, s2
	s_cmpk_lt_i32 s8, 0x4000
	s_cselect_b64 s[10:11], -1, 0
	s_and_b64 s[30:31], s[10:11], exec
	s_cselect_b32 s30, s8, s2
	s_ashr_i32 s31, s30, 31
	s_lshl_b64 s[34:35], s[30:31], 6
	s_add_u32 s34, s4, s34
	s_addc_u32 s35, s5, s35
	global_load_dwordx4 v[116:119], v97, s[34:35]
	global_load_dwordx4 v[120:123], v97, s[34:35] offset:16
	global_load_dwordx4 v[124:127], v97, s[34:35] offset:32
	global_load_dwordx4 v[128:131], v97, s[34:35] offset:48
	s_waitcnt vmcnt(0)
	v_lshl_add_u64 v[148:149], v[98:99], 0, s[0:1]
	v_lshl_add_u64 v[16:17], v[98:99], 0, s[24:25]
	global_load_dwordx4 v[132:135], v[148:149], off
	global_load_dwordx4 v[136:139], v[148:149], off offset:1024
	global_load_dwordx4 v[140:143], v[148:149], off offset:2048
	global_load_dwordx4 v[144:147], v[148:149], off offset:3072
	global_load_dwordx4 v[80:83], v97, s[22:23] offset:48
	global_load_dwordx4 v[84:87], v97, s[22:23] offset:32
	global_load_dwordx4 v[88:91], v97, s[22:23] offset:16
	global_load_dwordx4 v[92:95], v97, s[22:23]
	global_load_dwordx4 v[76:79], v[16:17], off
	global_load_dwordx4 v[72:75], v[16:17], off offset:1024
	global_load_dwordx4 v[68:71], v[16:17], off offset:2048
	global_load_dwordx4 v[64:67], v[16:17], off offset:3072
	global_load_dwordx4 v[48:51], v97, s[26:27] offset:48
	global_load_dwordx4 v[52:55], v97, s[26:27] offset:32
	global_load_dwordx4 v[56:59], v97, s[26:27] offset:16
	global_load_dwordx4 v[60:63], v97, s[26:27]
	v_lshl_add_u64 v[16:17], v[98:99], 0, s[28:29]
	s_lshl_b64 s[0:1], s[30:31], 12
	global_load_dwordx4 v[44:47], v[16:17], off
	global_load_dwordx4 v[40:43], v[16:17], off offset:1024
	global_load_dwordx4 v[36:39], v[16:17], off offset:2048
	global_load_dwordx4 v[32:35], v[16:17], off offset:3072
	v_lshl_add_u64 v[16:17], v[98:99], 0, s[0:1]
	global_load_dwordx4 v[28:31], v[16:17], off
	global_load_dwordx4 v[24:27], v[16:17], off offset:1024
	global_load_dwordx4 v[20:23], v[16:17], off offset:2048
	s_nop 0
	global_load_dwordx4 v[16:19], v[16:17], off offset:3072
	s_cmpk_gt_i32 s16, 0x3fff
	v_add_f32_e32 v104, v104, v105
	v_add_f32_e32 v106, v106, v107
	v_mov_b32_e32 v150, v113
	v_mov_b32_e32 v151, v114
	v_mov_b32_e32 v113, v115
	v_mov_b32_e32 v114, v109
	v_mov_b32_e32 v115, v110
	v_mov_b32_e32 v109, v111
	v_mov_b32_e32 v105, v102
	v_mov_b32_e32 v107, v103
	v_add_f32_e32 v102, v150, v112
	v_add_f32_e32 v103, v151, v113
	v_add_f32_e32 v108, v114, v108
	v_add_f32_e32 v109, v115, v109
	v_add_f32_e32 v104, v104, v106
	v_add_f32_e32 v105, v105, v107
	v_pk_add_f32 v[102:103], v[102:103], v[102:103] op_sel:[0,1] op_sel_hi:[1,0]
	v_pk_add_f32 v[106:107], v[108:109], v[108:109] op_sel:[0,1] op_sel_hi:[1,0]
	v_mov_b32_e32 v103, v100
	v_mov_b32_e32 v107, v101
	v_add_f32_e32 v100, v102, v106
	v_add_f32_e32 v101, v103, v107
	v_mov_b32_e32 v106, v121
	v_add_f32_e32 v100, v100, v104
	v_add_f32_e32 v101, v101, v105
	v_mov_b32_e32 v104, v117
	v_mov_b32_e32 v105, v118
	v_mov_b32_e32 v117, v119
	v_mov_b32_e32 v107, v122
	v_mov_b32_e32 v121, v123
	v_add_f32_e32 v104, v104, v116
	v_add_f32_e32 v105, v105, v117
	v_add_f32_e32 v106, v106, v120
	v_add_f32_e32 v107, v107, v121
	v_pk_add_f32 v[104:105], v[104:105], v[104:105] op_sel:[0,1] op_sel_hi:[1,0]
	v_pk_add_f32 v[106:107], v[106:107], v[106:107] op_sel:[0,1] op_sel_hi:[1,0]
	v_add_f32_e32 v108, v124, v125
	v_add_f32_e32 v110, v126, v127
	v_mov_b32_e32 v109, v130
	v_mov_b32_e32 v111, v131
	v_mov_b32_e32 v105, v128
	v_mov_b32_e32 v107, v129
	v_add_f32_e32 v108, v108, v110
	v_add_f32_e32 v109, v109, v111
	v_add_f32_e32 v104, v104, v106
	v_add_f32_e32 v105, v105, v107
	v_mov_b32_e32 v102, v100
	v_add_f32_e32 v104, v104, v108
	v_add_f32_e32 v105, v105, v109
	s_nop 0
	v_mov_b32_e32 v103, v104
	v_mov_b32_e32 v104, v101
	v_add_f32_e32 v100, v102, v104
	v_add_f32_e32 v101, v103, v105
	s_nop 0
	v_pk_fma_f32 v[100:101], v[100:101], s[6:7], v[96:97] op_sel_hi:[1,0,0]
	s_nop 0
	v_mul_f32_e32 v102, 0x4b800000, v100
	v_cmp_gt_f32_e32 vcc, s21, v100
	v_cmp_gt_f32_e64 s[0:1], s21, v101
	s_nop 0
	v_cndmask_b32_e32 v100, v100, v102, vcc
	v_rsq_f32_e32 v100, v100
	s_nop 0
	v_mul_f32_e32 v102, 0x45800000, v100
	v_cndmask_b32_e32 v100, v100, v102, vcc
	s_waitcnt vmcnt(23)
	v_pk_mul_f32 v[102:103], v[100:101], v[132:133] op_sel_hi:[0,1]
	v_pk_mul_f32 v[104:105], v[100:101], v[134:135] op_sel_hi:[0,1]
	v_mul_f32_e32 v104, v2, v104
	v_mul_f32_e32 v105, v3, v105
	v_mul_f32_e32 v102, v0, v102
	v_mul_f32_e32 v103, v1, v103
	global_store_dwordx4 v[148:149], v[102:105], off
	s_waitcnt vmcnt(23)
	s_nop 0
	v_pk_mul_f32 v[102:103], v[100:101], v[136:137] op_sel_hi:[0,1]
	v_pk_mul_f32 v[104:105], v[100:101], v[138:139] op_sel_hi:[0,1]
	v_mul_f32_e32 v104, v6, v104
	v_mul_f32_e32 v105, v7, v105
	v_mul_f32_e32 v102, v4, v102
	v_mul_f32_e32 v103, v5, v103
	global_store_dwordx4 v[148:149], v[102:105], off offset:1024
	s_waitcnt vmcnt(23)
	s_nop 0
	v_pk_mul_f32 v[102:103], v[100:101], v[140:141] op_sel_hi:[0,1]
	v_pk_mul_f32 v[104:105], v[100:101], v[142:143] op_sel_hi:[0,1]
	v_mul_f32_e32 v104, v10, v104
	v_mul_f32_e32 v105, v11, v105
	v_mul_f32_e32 v102, v8, v102
	v_mul_f32_e32 v103, v9, v103
	global_store_dwordx4 v[148:149], v[102:105], off offset:2048
	s_waitcnt vmcnt(23)
	s_nop 0
	v_pk_mul_f32 v[102:103], v[100:101], v[144:145] op_sel_hi:[0,1]
	v_pk_mul_f32 v[104:105], v[100:101], v[146:147] op_sel_hi:[0,1]
	v_mul_f32_e32 v104, v14, v104
	v_mul_f32_e32 v105, v15, v105
	v_mul_f32_e32 v102, v12, v102
	v_mul_f32_e32 v103, v13, v103
	global_store_dwordx4 v[148:149], v[102:105], off offset:3072
	s_cbranch_scc1 .LBB0_1478
	s_waitcnt vmcnt(20)
	v_mov_b32_e32 v102, v93
	v_mov_b32_e32 v103, v94
	v_mov_b32_e32 v93, v95
	v_mov_b32_e32 v94, v89
	v_mov_b32_e32 v95, v90
	v_mov_b32_e32 v89, v91
	v_add_f32_e32 v92, v102, v92
	v_add_f32_e32 v93, v103, v93
	v_add_f32_e32 v88, v94, v88
	v_add_f32_e32 v89, v95, v89
	v_pk_add_f32 v[92:93], v[92:93], v[92:93] op_sel:[0,1] op_sel_hi:[1,0]
	v_pk_add_f32 v[88:89], v[88:89], v[88:89] op_sel:[0,1] op_sel_hi:[1,0]
	v_add_f32_e32 v84, v84, v85
	v_add_f32_e32 v86, v86, v87
	v_mov_b32_e32 v93, v80
	v_mov_b32_e32 v89, v81
	v_mov_b32_e32 v85, v82
	v_mov_b32_e32 v87, v83
	v_add_f32_e32 v80, v92, v88
	v_add_f32_e32 v81, v93, v89
	v_add_f32_e32 v82, v84, v86
	v_add_f32_e32 v83, v85, v87
	s_ashr_i32 s17, s16, 31
	v_add_f32_e32 v80, v80, v82
	v_add_f32_e32 v81, v81, v83
	s_lshl_b64 s[16:17], s[16:17], 12
	v_add_f32_e32 v80, v80, v81
	v_fmamk_f32 v80, v80, 0x3a800000, v96
	v_mul_f32_e32 v81, 0x4b800000, v80
	v_cmp_gt_f32_e32 vcc, s21, v80
	v_lshl_add_u64 v[82:83], v[98:99], 0, s[16:17]
	s_nop 0
	v_cndmask_b32_e32 v80, v80, v81, vcc
	v_rsq_f32_e32 v80, v80
	s_nop 0
	v_mul_f32_e32 v81, 0x45800000, v80
	v_cndmask_b32_e32 v80, v80, v81, vcc
	s_waitcnt vmcnt(19)
	v_pk_mul_f32 v[76:77], v[80:81], v[76:77] op_sel_hi:[0,1]
	v_pk_mul_f32 v[78:79], v[80:81], v[78:79] op_sel_hi:[0,1]
	s_waitcnt vmcnt(18)
	v_pk_mul_f32 v[72:73], v[80:81], v[72:73] op_sel_hi:[0,1]
	v_pk_mul_f32 v[74:75], v[80:81], v[74:75] op_sel_hi:[0,1]
	s_waitcnt vmcnt(17)
	v_pk_mul_f32 v[68:69], v[80:81], v[68:69] op_sel_hi:[0,1]
	v_pk_mul_f32 v[70:71], v[80:81], v[70:71] op_sel_hi:[0,1]
	s_waitcnt vmcnt(16)
	v_pk_mul_f32 v[64:65], v[80:81], v[64:65] op_sel_hi:[0,1]
	v_pk_mul_f32 v[66:67], v[80:81], v[66:67] op_sel_hi:[0,1]
	v_mul_f32_e32 v78, v2, v78
	v_mul_f32_e32 v79, v3, v79
	v_mul_f32_e32 v76, v0, v76
	v_mul_f32_e32 v77, v1, v77
	v_mul_f32_e32 v74, v6, v74
	v_mul_f32_e32 v75, v7, v75
	v_mul_f32_e32 v72, v4, v72
	v_mul_f32_e32 v73, v5, v73
	v_mul_f32_e32 v70, v10, v70
	v_mul_f32_e32 v71, v11, v71
	v_mul_f32_e32 v68, v8, v68
	v_mul_f32_e32 v69, v9, v69
	v_mul_f32_e32 v66, v14, v66
	v_mul_f32_e32 v67, v15, v67
	v_mul_f32_e32 v64, v12, v64
	v_mul_f32_e32 v65, v13, v65
	global_store_dwordx4 v[82:83], v[76:79], off
	global_store_dwordx4 v[82:83], v[72:75], off offset:1024
	global_store_dwordx4 v[82:83], v[68:71], off offset:2048
	global_store_dwordx4 v[82:83], v[64:67], off offset:3072
	s_andn2_b64 vcc, exec, s[14:15]
	s_cbranch_vccz .LBB0_1479

.LBB0_1479:
	s_waitcnt vmcnt(12)
	v_mov_b32_e32 v64, v61
	v_mov_b32_e32 v65, v62
	v_mov_b32_e32 v61, v63
	v_mov_b32_e32 v62, v57
	v_mov_b32_e32 v63, v58
	v_mov_b32_e32 v57, v59
	v_add_f32_e32 v60, v64, v60
	v_add_f32_e32 v61, v65, v61
	v_add_f32_e32 v56, v62, v56
	v_add_f32_e32 v57, v63, v57
	v_pk_add_f32 v[60:61], v[60:61], v[60:61] op_sel:[0,1] op_sel_hi:[1,0]
	v_pk_add_f32 v[56:57], v[56:57], v[56:57] op_sel:[0,1] op_sel_hi:[1,0]
	v_add_f32_e32 v52, v52, v53
	v_add_f32_e32 v54, v54, v55
	v_mov_b32_e32 v61, v48
	v_mov_b32_e32 v57, v49
	v_mov_b32_e32 v53, v50
	v_mov_b32_e32 v55, v51
	v_add_f32_e32 v48, v60, v56
	v_add_f32_e32 v49, v61, v57
	v_add_f32_e32 v50, v52, v54
	v_add_f32_e32 v51, v53, v55
	s_ashr_i32 s13, s12, 31
	v_add_f32_e32 v48, v48, v50
	v_add_f32_e32 v49, v49, v51
	s_lshl_b64 s[12:13], s[12:13], 12
	v_add_f32_e32 v48, v48, v49
	v_fmamk_f32 v48, v48, 0x3a800000, v96
	v_mul_f32_e32 v49, 0x4b800000, v48
	v_cmp_gt_f32_e32 vcc, s21, v48
	v_lshl_add_u64 v[50:51], v[98:99], 0, s[12:13]
	s_nop 0
	v_cndmask_b32_e32 v48, v48, v49, vcc
	v_rsq_f32_e32 v48, v48
	s_nop 0
	v_mul_f32_e32 v49, 0x45800000, v48
	v_cndmask_b32_e32 v48, v48, v49, vcc
	s_waitcnt vmcnt(11)
	v_pk_mul_f32 v[44:45], v[48:49], v[44:45] op_sel_hi:[0,1]
	v_pk_mul_f32 v[46:47], v[48:49], v[46:47] op_sel_hi:[0,1]
	s_waitcnt vmcnt(10)
	v_pk_mul_f32 v[40:41], v[48:49], v[40:41] op_sel_hi:[0,1]
	v_pk_mul_f32 v[42:43], v[48:49], v[42:43] op_sel_hi:[0,1]
	s_waitcnt vmcnt(9)
	v_pk_mul_f32 v[36:37], v[48:49], v[36:37] op_sel_hi:[0,1]
	v_pk_mul_f32 v[38:39], v[48:49], v[38:39] op_sel_hi:[0,1]
	s_waitcnt vmcnt(8)
	v_pk_mul_f32 v[32:33], v[48:49], v[32:33] op_sel_hi:[0,1]
	v_pk_mul_f32 v[34:35], v[48:49], v[34:35] op_sel_hi:[0,1]
	v_mul_f32_e32 v46, v2, v46
	v_mul_f32_e32 v47, v3, v47
	v_mul_f32_e32 v44, v0, v44
	v_mul_f32_e32 v45, v1, v45
	v_mul_f32_e32 v42, v6, v42
	v_mul_f32_e32 v43, v7, v43
	v_mul_f32_e32 v40, v4, v40
	v_mul_f32_e32 v41, v5, v41
	v_mul_f32_e32 v38, v10, v38
	v_mul_f32_e32 v39, v11, v39
	v_mul_f32_e32 v36, v8, v36
	v_mul_f32_e32 v37, v9, v37
	v_mul_f32_e32 v34, v14, v34
	v_mul_f32_e32 v35, v15, v35
	v_mul_f32_e32 v32, v12, v32
	v_mul_f32_e32 v33, v13, v33
	global_store_dwordx4 v[50:51], v[44:47], off
	global_store_dwordx4 v[50:51], v[40:43], off offset:1024
	global_store_dwordx4 v[50:51], v[36:39], off offset:2048
	global_store_dwordx4 v[50:51], v[32:35], off offset:3072
	s_andn2_b64 vcc, exec, s[10:11]
	s_cbranch_vccnz .LBB0_1474
.LBB0_1480:
	s_waitcnt vmcnt(8)
	v_mul_f32_e32 v32, 0x4b800000, v101
	v_cndmask_b32_e64 v32, v101, v32, s[0:1]
	v_rsq_f32_e32 v32, v32
	s_ashr_i32 s9, s8, 31
	s_lshl_b64 s[8:9], s[8:9], 12
	v_lshl_add_u64 v[34:35], v[98:99], 0, s[8:9]
	v_mul_f32_e32 v33, 0x45800000, v32
	v_cndmask_b32_e64 v32, v32, v33, s[0:1]
	s_waitcnt vmcnt(7)
	v_pk_mul_f32 v[28:29], v[32:33], v[28:29] op_sel_hi:[0,1]
	v_pk_mul_f32 v[30:31], v[32:33], v[30:31] op_sel_hi:[0,1]
	s_waitcnt vmcnt(6)
	v_pk_mul_f32 v[24:25], v[32:33], v[24:25] op_sel_hi:[0,1]
	v_pk_mul_f32 v[26:27], v[32:33], v[26:27] op_sel_hi:[0,1]
	s_waitcnt vmcnt(5)
	v_pk_mul_f32 v[20:21], v[32:33], v[20:21] op_sel_hi:[0,1]
	v_pk_mul_f32 v[22:23], v[32:33], v[22:23] op_sel_hi:[0,1]
	s_waitcnt vmcnt(4)
	v_pk_mul_f32 v[16:17], v[32:33], v[16:17] op_sel_hi:[0,1]
	v_pk_mul_f32 v[18:19], v[32:33], v[18:19] op_sel_hi:[0,1]
	v_mul_f32_e32 v30, v2, v30
	v_mul_f32_e32 v31, v3, v31
	v_mul_f32_e32 v28, v0, v28
	v_mul_f32_e32 v29, v1, v29
	v_mul_f32_e32 v26, v6, v26
	v_mul_f32_e32 v27, v7, v27
	v_mul_f32_e32 v24, v4, v24
	v_mul_f32_e32 v25, v5, v25
	v_mul_f32_e32 v22, v10, v22
	v_mul_f32_e32 v23, v11, v23
	v_mul_f32_e32 v20, v8, v20
	v_mul_f32_e32 v21, v9, v21
	v_mul_f32_e32 v18, v14, v18
	v_mul_f32_e32 v19, v15, v19
	v_mul_f32_e32 v16, v12, v16
	v_mul_f32_e32 v17, v13, v17
	global_store_dwordx4 v[34:35], v[28:31], off
	global_store_dwordx4 v[34:35], v[24:27], off offset:1024
	global_store_dwordx4 v[34:35], v[20:23], off offset:2048
	global_store_dwordx4 v[34:35], v[16:19], off offset:3072
	s_branch .LBB0_1474
